# GLA pre-pass sequential decay pass: LDS reads issued one token-pair block ahead into spare VGPRs, counted lgkmcnt waits re-derived
# speedup vs baseline: 1.0006x; 1.0006x over previous
.LBB0_418:
	s_or_b64 exec, exec, s[4:5]
	v_lshl_or_b32 v36, v98, 2, s27
	v_or_b32_e32 v37, 16, v87
	v_or_b32_e32 v38, 3, v36
	v_add_f32_e32 v34, 0, v71
	v_cmp_le_u32_e32 vcc, v37, v38
	v_or_b32_e32 v40, 2, v36
	v_add_f32_e32 v35, 0, v69
	v_cndmask_b32_e32 v39, 0, v34, vcc
	v_add_f32_e32 v34, 0, v70
	v_cmp_le_u32_e32 vcc, v37, v40
	v_cmp_le_u32_e64 s[4:5], v87, v38
	s_nop 0
	v_cndmask_b32_e32 v41, 0, v34, vcc
	v_or_b32_e32 v34, 1, v36
	v_cmp_le_u32_e32 vcc, v37, v34
	s_barrier
	s_waitcnt lgkmcnt(0)
	s_nop 0
	v_cndmask_b32_e32 v42, 0, v35, vcc
	v_add_f32_e32 v35, 0, v68
	v_cmp_gt_u32_e32 vcc, v37, v36
	v_mul_u32_u24_e32 v47, 0x210, v87
	v_add_f32_e32 v64, 0, v64
	v_cndmask_b32_e64 v43, v35, 0, vcc
	v_add_f32_e32 v35, 0, v67
	v_cndmask_b32_e64 v44, 0, v35, s[4:5]
	v_add_f32_e32 v35, 0, v66
	v_cmp_le_u32_e64 s[4:5], v87, v40
	ds_read_u16 v154, v99 offset:15840
	ds_read_u16 v155, v99 offset:16368
	ds_read_u16 v156, v99 offset:49632
	ds_read_u16 v157, v99 offset:50160
	ds_read_u16 v158, v99 offset:15312
	ds_read_u16 v159, v99 offset:14784
	ds_read_u16 v160, v99 offset:48576
	ds_read_u16 v161, v99 offset:49104
	s_waitcnt lgkmcnt(7)
	v_lshlrev_b32_e32 v66, 16, v154
	v_cndmask_b32_e64 v45, 0, v35, s[4:5]
	v_add_f32_e32 v35, 0, v65
	v_cmp_le_u32_e64 s[4:5], v87, v34
	v_mul_f32_e32 v68, 0x3d800000, v66
	v_cndmask_b32_e64 v46, 0, v35, s[4:5]
	v_cmp_ne_u32_e64 s[4:5], 1, v101
	s_waitcnt lgkmcnt(6)
	v_lshlrev_b32_e32 v65, 16, v155
	v_cndmask_b32_e64 v33, 0, v33, s[4:5]
	v_add_f32_e32 v48, v48, v33
	v_mul_f32_e32 v48, 0x3fb8aa3b, v48
	v_exp_f32_e32 v48, v48
	v_mul_f32_e32 v65, 0x3d800000, v65
	s_lshl_b64 s[4:5], s[14:15], 15
	s_add_u32 s4, s43, s4
	v_rcp_f32_e32 v67, v48
	v_mul_f32_e32 v48, v48, v65
	v_cvt_pk_bf16_f32 v48, v48, s0
	ds_write_b16 v99, v48 offset:16368
	v_add_f32_e32 v48, v49, v33
	v_mul_f32_e32 v48, 0x3fb8aa3b, v48
	v_exp_f32_e32 v48, v48
	s_addc_u32 s5, s44, s5
	v_lshl_add_u64 v[34:35], s[4:5], 0, v[84:85]
	v_rcp_f32_e32 v66, v48
	v_mul_f32_e32 v68, v48, v68
	s_waitcnt lgkmcnt(5)
	v_lshlrev_b32_e32 v49, 16, v157
	v_lshlrev_b32_e32 v48, 16, v156
	v_pk_mul_f32 v[48:49], v[66:67], v[48:49]
	v_lshl_add_u64 v[34:35], v[82:83], 1, v[34:35]
	v_cvt_pk_bf16_f32 v65, v49, s0
	v_pk_mul_f32 v[66:67], v[32:33], v[48:49] op_sel_hi:[0,1]
	v_cvt_pk_bf16_f32 v49, v68, s0
	v_cvt_pk_bf16_f32 v48, v48, s0
	ds_write_b16 v99, v65 offset:50160
	ds_write_b16 v99, v49 offset:15840
	ds_write_b16 v99, v48 offset:49632
	ds_read_u16 v154, v99 offset:14256
	ds_read_u16 v155, v99 offset:13728
	ds_read_u16 v156, v99 offset:47520
	ds_read_u16 v157, v99 offset:48048
	v_add_f32_e32 v49, v50, v33
	v_mul_f32_e32 v49, 0x3fb8aa3b, v49
	v_exp_f32_e32 v50, v49
	s_waitcnt lgkmcnt(11)
	v_lshlrev_b32_e32 v48, 16, v158
	v_mul_f32_e32 v48, 0x3d800000, v48
	v_cmp_gt_u32_e64 s[4:5], v87, v36
	v_mul_f32_e32 v48, v50, v48
	v_cvt_pk_bf16_f32 v48, v48, s0
	ds_write_b16 v99, v48 offset:15312
	v_add_f32_e32 v48, v51, v33
	v_mul_f32_e32 v48, 0x3fb8aa3b, v48
	v_rcp_f32_e32 v49, v50
	v_exp_f32_e32 v50, v48
	s_waitcnt lgkmcnt(11)
	v_lshlrev_b32_e32 v48, 16, v159
	v_mul_f32_e32 v65, 0x3d800000, v48
	v_rcp_f32_e32 v48, v50
	v_mul_f32_e32 v65, v50, v65
	s_waitcnt lgkmcnt(9)
	v_lshlrev_b32_e32 v51, 16, v161
	v_lshlrev_b32_e32 v50, 16, v160
	v_pk_mul_f32 v[48:49], v[48:49], v[50:51]
	s_add_u32 s1, s49, s6
	v_cvt_pk_bf16_f32 v50, v49, s0
	ds_write_b16 v99, v50 offset:49104
	v_pk_mul_f32 v[50:51], v[32:33], v[48:49] op_sel_hi:[0,1]
	v_cvt_pk_bf16_f32 v49, v65, s0
	v_cvt_pk_bf16_f32 v48, v48, s0
	ds_write_b16 v99, v49 offset:14784
	ds_write_b16 v99, v48 offset:48576
	ds_read_u16 v158, v99 offset:13200
	ds_read_u16 v159, v99 offset:12672
	ds_read_u16 v160, v99 offset:46464
	ds_read_u16 v161, v99 offset:46992
	v_add_f32_e32 v49, v52, v33
	v_mul_f32_e32 v49, 0x3fb8aa3b, v49
	v_exp_f32_e32 v52, v49
	s_waitcnt lgkmcnt(11)
	v_lshlrev_b32_e32 v48, 16, v154
	v_mul_f32_e32 v48, 0x3d800000, v48
	v_cvt_pk_bf16_f32 v50, v50, v51
	v_mul_f32_e32 v48, v52, v48
	v_cvt_pk_bf16_f32 v48, v48, s0
	ds_write_b16 v99, v48 offset:14256
	v_add_f32_e32 v48, v53, v33
	v_mul_f32_e32 v48, 0x3fb8aa3b, v48
	v_rcp_f32_e32 v49, v52
	v_exp_f32_e32 v52, v48
	s_waitcnt lgkmcnt(11)
	v_lshlrev_b32_e32 v48, 16, v155
	v_mul_f32_e32 v65, 0x3d800000, v48
	v_rcp_f32_e32 v48, v52
	v_mul_f32_e32 v65, v52, v65
	s_waitcnt lgkmcnt(9)
	v_lshlrev_b32_e32 v53, 16, v157
	v_lshlrev_b32_e32 v52, 16, v156
	v_pk_mul_f32 v[48:49], v[48:49], v[52:53]
	v_cvt_pk_bf16_f32 v51, v66, v67
	v_cvt_pk_bf16_f32 v52, v49, s0
	ds_write_b16 v99, v52 offset:48048
	v_pk_mul_f32 v[52:53], v[32:33], v[48:49] op_sel_hi:[0,1]
	v_cvt_pk_bf16_f32 v49, v65, s0
	v_cvt_pk_bf16_f32 v48, v48, s0
	ds_write_b16 v99, v49 offset:13728
	ds_write_b16 v99, v48 offset:47520
	ds_read_u16 v154, v99 offset:12144
	ds_read_u16 v155, v99 offset:11616
	ds_read_u16 v156, v99 offset:45408
	ds_read_u16 v157, v99 offset:45936
	v_add_f32_e32 v49, v54, v33
	v_mul_f32_e32 v49, 0x3fb8aa3b, v49
	v_exp_f32_e32 v54, v49
	s_waitcnt lgkmcnt(11)
	v_lshlrev_b32_e32 v48, 16, v158
	v_mul_f32_e32 v48, 0x3d800000, v48
	s_addc_u32 s6, s52, s7
	v_mul_f32_e32 v48, v54, v48
	v_cvt_pk_bf16_f32 v48, v48, s0
	ds_write_b16 v99, v48 offset:13200
	v_add_f32_e32 v48, v56, v33
	v_mul_f32_e32 v48, 0x3fb8aa3b, v48
	v_rcp_f32_e32 v49, v54
	v_exp_f32_e32 v54, v48
	s_waitcnt lgkmcnt(11)
	v_lshlrev_b32_e32 v48, 16, v159
	v_mul_f32_e32 v65, 0x3d800000, v48
	v_rcp_f32_e32 v48, v54
	v_mul_f32_e32 v54, v54, v65
	s_waitcnt lgkmcnt(9)
	v_lshlrev_b32_e32 v69, 16, v161
	v_lshlrev_b32_e32 v68, 16, v160
	v_pk_mul_f32 v[48:49], v[48:49], v[68:69]
	s_nop 0
	v_cvt_pk_bf16_f32 v56, v49, s0
	v_pk_mul_f32 v[68:69], v[32:33], v[48:49] op_sel_hi:[0,1]
	v_cvt_pk_bf16_f32 v49, v54, s0
	v_cvt_pk_bf16_f32 v48, v48, s0
	ds_write_b16 v99, v56 offset:46992
	ds_write_b16 v99, v49 offset:12672
	ds_write_b16 v99, v48 offset:46464
	v_cvt_pk_bf16_f32 v48, v68, v69
	v_cvt_pk_bf16_f32 v49, v52, v53
	global_store_dwordx4 v[34:35], v[48:51], off offset:48
	ds_read_u16 v158, v99 offset:11088
	ds_read_u16 v159, v99 offset:10560
	ds_read_u16 v160, v99 offset:44352
	ds_read_u16 v161, v99 offset:44880
	v_add_f32_e32 v49, v55, v33
	v_mul_f32_e32 v49, 0x3fb8aa3b, v49
	v_exp_f32_e32 v50, v49
	s_waitcnt lgkmcnt(11)
	v_lshlrev_b32_e32 v48, 16, v154
	v_mul_f32_e32 v48, 0x3d800000, v48
	v_mul_f32_e32 v48, v50, v48
	v_cvt_pk_bf16_f32 v48, v48, s0
	ds_write_b16 v99, v48 offset:12144
	v_add_f32_e32 v48, v57, v33
	v_mul_f32_e32 v48, 0x3fb8aa3b, v48
	v_rcp_f32_e32 v49, v50
	v_exp_f32_e32 v50, v48
	s_waitcnt lgkmcnt(11)
	v_lshlrev_b32_e32 v48, 16, v155
	v_mul_f32_e32 v51, 0x3d800000, v48
	v_rcp_f32_e32 v48, v50
	v_mul_f32_e32 v54, v50, v51
	s_waitcnt lgkmcnt(9)
	v_lshlrev_b32_e32 v51, 16, v157
	v_lshlrev_b32_e32 v50, 16, v156
	v_pk_mul_f32 v[48:49], v[48:49], v[50:51]
	s_nop 0
	v_cvt_pk_bf16_f32 v50, v49, s0
	v_pk_mul_f32 v[52:53], v[32:33], v[48:49] op_sel_hi:[0,1]
	v_cvt_pk_bf16_f32 v49, v54, s0
	v_cvt_pk_bf16_f32 v48, v48, s0
	ds_write_b16 v99, v50 offset:45936
	ds_write_b16 v99, v49 offset:11616
	ds_write_b16 v99, v48 offset:45408
	ds_read_u16 v154, v99 offset:10032
	ds_read_u16 v155, v99 offset:9504
	ds_read_u16 v156, v99 offset:43296
	ds_read_u16 v157, v99 offset:43824
	v_add_f32_e32 v49, v58, v33
	v_mul_f32_e32 v49, 0x3fb8aa3b, v49
	v_exp_f32_e32 v50, v49
	s_waitcnt lgkmcnt(11)
	v_lshlrev_b32_e32 v48, 16, v158
	v_mul_f32_e32 v48, 0x3d800000, v48
	v_mul_f32_e32 v48, v50, v48
	v_cvt_pk_bf16_f32 v48, v48, s0
	ds_write_b16 v99, v48 offset:11088
	v_add_f32_e32 v48, v59, v33
	v_mul_f32_e32 v48, 0x3fb8aa3b, v48
	v_rcp_f32_e32 v49, v50
	v_exp_f32_e32 v50, v48
	s_waitcnt lgkmcnt(11)
	v_lshlrev_b32_e32 v48, 16, v159
	v_mul_f32_e32 v51, 0x3d800000, v48
	v_rcp_f32_e32 v48, v50
	v_mul_f32_e32 v56, v50, v51
	s_waitcnt lgkmcnt(9)
	v_lshlrev_b32_e32 v51, 16, v161
	v_lshlrev_b32_e32 v50, 16, v160
	v_pk_mul_f32 v[48:49], v[48:49], v[50:51]
	s_nop 0
	v_cvt_pk_bf16_f32 v50, v49, s0
	ds_write_b16 v99, v50 offset:44880
	v_pk_mul_f32 v[50:51], v[32:33], v[48:49] op_sel_hi:[0,1]
	v_cvt_pk_bf16_f32 v49, v56, s0
	v_cvt_pk_bf16_f32 v48, v48, s0
	ds_write_b16 v99, v49 offset:10560
	ds_write_b16 v99, v48 offset:44352
	ds_read_u16 v158, v99 offset:8976
	ds_read_u16 v159, v99 offset:8448
	ds_read_u16 v160, v99 offset:42240
	ds_read_u16 v161, v99 offset:42768
	v_add_f32_e32 v49, v60, v33
	v_mul_f32_e32 v49, 0x3fb8aa3b, v49
	v_exp_f32_e32 v54, v49
	s_waitcnt lgkmcnt(11)
	v_lshlrev_b32_e32 v48, 16, v154
	v_mul_f32_e32 v48, 0x3d800000, v48
	v_cvt_pk_bf16_f32 v50, v50, v51
	v_mul_f32_e32 v48, v54, v48
	v_cvt_pk_bf16_f32 v48, v48, s0
	ds_write_b16 v99, v48 offset:10032
	v_add_f32_e32 v48, v61, v33
	v_mul_f32_e32 v48, 0x3fb8aa3b, v48
	v_rcp_f32_e32 v49, v54
	v_exp_f32_e32 v54, v48
	s_waitcnt lgkmcnt(11)
	v_lshlrev_b32_e32 v48, 16, v155
	v_mul_f32_e32 v55, 0x3d800000, v48
	v_rcp_f32_e32 v48, v54
	v_mul_f32_e32 v58, v54, v55
	s_waitcnt lgkmcnt(9)
	v_lshlrev_b32_e32 v55, 16, v157
	v_lshlrev_b32_e32 v54, 16, v156
	v_pk_mul_f32 v[48:49], v[48:49], v[54:55]
	v_cvt_pk_bf16_f32 v51, v52, v53
	v_cvt_pk_bf16_f32 v54, v49, s0
	ds_write_b16 v99, v54 offset:43824
	v_pk_mul_f32 v[54:55], v[32:33], v[48:49] op_sel_hi:[0,1]
	v_cvt_pk_bf16_f32 v49, v58, s0
	v_cvt_pk_bf16_f32 v48, v48, s0
	ds_write_b16 v99, v49 offset:9504
	ds_write_b16 v99, v48 offset:43296
	ds_read_u16 v154, v99 offset:7920
	ds_read_u16 v155, v99 offset:7392
	ds_read_u16 v156, v99 offset:41184
	ds_read_u16 v157, v99 offset:41712
	v_add_f32_e32 v49, v62, v33
	v_mul_f32_e32 v49, 0x3fb8aa3b, v49
	v_exp_f32_e32 v56, v49
	s_waitcnt lgkmcnt(11)
	v_lshlrev_b32_e32 v48, 16, v158
	v_mul_f32_e32 v48, 0x3d800000, v48
	v_mul_f32_e32 v48, v56, v48
	v_cvt_pk_bf16_f32 v48, v48, s0
	ds_write_b16 v99, v48 offset:8976
	v_add_f32_e32 v48, v89, v33
	v_mul_f32_e32 v48, 0x3fb8aa3b, v48
	v_rcp_f32_e32 v49, v56
	v_exp_f32_e32 v56, v48
	s_waitcnt lgkmcnt(11)
	v_lshlrev_b32_e32 v48, 16, v159
	v_mul_f32_e32 v57, 0x3d800000, v48
	v_rcp_f32_e32 v48, v56
	v_mul_f32_e32 v60, v56, v57
	s_waitcnt lgkmcnt(9)
	v_lshlrev_b32_e32 v57, 16, v161
	v_lshlrev_b32_e32 v56, 16, v160
	v_pk_mul_f32 v[48:49], v[48:49], v[56:57]
	s_nop 0
	v_cvt_pk_bf16_f32 v56, v49, s0
	ds_write_b16 v99, v56 offset:42768
	v_pk_mul_f32 v[56:57], v[32:33], v[48:49] op_sel_hi:[0,1]
	v_cvt_pk_bf16_f32 v49, v60, s0
	v_cvt_pk_bf16_f32 v48, v48, s0
	ds_write_b16 v99, v49 offset:8448
	ds_write_b16 v99, v48 offset:42240
	v_cvt_pk_bf16_f32 v48, v56, v57
	v_cvt_pk_bf16_f32 v49, v54, v55
	global_store_dwordx4 v[34:35], v[48:51], off offset:32
	ds_read_u16 v158, v99 offset:6864
	ds_read_u16 v159, v99 offset:6336
	ds_read_u16 v160, v99 offset:40128
	ds_read_u16 v161, v99 offset:40656
	v_add_f32_e32 v49, v63, v33
	v_mul_f32_e32 v49, 0x3fb8aa3b, v49
	v_exp_f32_e32 v50, v49
	s_waitcnt lgkmcnt(11)
	v_lshlrev_b32_e32 v48, 16, v154
	v_mul_f32_e32 v48, 0x3d800000, v48
	v_mul_f32_e32 v48, v50, v48
	v_cvt_pk_bf16_f32 v48, v48, s0
	ds_write_b16 v99, v48 offset:7920
	v_add_f32_e32 v48, v90, v33
	v_mul_f32_e32 v48, 0x3fb8aa3b, v48
	v_rcp_f32_e32 v49, v50
	v_exp_f32_e32 v50, v48
	s_waitcnt lgkmcnt(11)
	v_lshlrev_b32_e32 v48, 16, v155
	v_mul_f32_e32 v51, 0x3d800000, v48
	v_rcp_f32_e32 v48, v50
	v_mul_f32_e32 v54, v50, v51
	s_waitcnt lgkmcnt(9)
	v_lshlrev_b32_e32 v51, 16, v157
	v_lshlrev_b32_e32 v50, 16, v156
	v_pk_mul_f32 v[48:49], v[48:49], v[50:51]
	s_nop 0
	v_cvt_pk_bf16_f32 v50, v49, s0
	v_pk_mul_f32 v[52:53], v[32:33], v[48:49] op_sel_hi:[0,1]
	v_cvt_pk_bf16_f32 v49, v54, s0
	v_cvt_pk_bf16_f32 v48, v48, s0
	ds_write_b16 v99, v50 offset:41712
	ds_write_b16 v99, v49 offset:7392
	ds_write_b16 v99, v48 offset:41184
	ds_read_u16 v154, v99 offset:5808
	ds_read_u16 v155, v99 offset:5280
	ds_read_u16 v156, v99 offset:39072
	ds_read_u16 v157, v99 offset:39600
	v_add_f32_e32 v49, v91, v33
	v_mul_f32_e32 v49, 0x3fb8aa3b, v49
	v_exp_f32_e32 v50, v49
	s_waitcnt lgkmcnt(11)
	v_lshlrev_b32_e32 v48, 16, v158
	v_mul_f32_e32 v48, 0x3d800000, v48
	v_mul_f32_e32 v48, v50, v48
	v_cvt_pk_bf16_f32 v48, v48, s0
	ds_write_b16 v99, v48 offset:6864
	v_add_f32_e32 v48, v106, v33
	v_mul_f32_e32 v48, 0x3fb8aa3b, v48
	v_rcp_f32_e32 v49, v50
	v_exp_f32_e32 v50, v48
	s_waitcnt lgkmcnt(11)
	v_lshlrev_b32_e32 v48, 16, v159
	v_mul_f32_e32 v51, 0x3d800000, v48
	v_rcp_f32_e32 v48, v50
	v_mul_f32_e32 v56, v50, v51
	s_waitcnt lgkmcnt(9)
	v_lshlrev_b32_e32 v51, 16, v161
	v_lshlrev_b32_e32 v50, 16, v160
	v_pk_mul_f32 v[48:49], v[48:49], v[50:51]
	s_nop 0
	v_cvt_pk_bf16_f32 v50, v49, s0
	ds_write_b16 v99, v50 offset:40656
	v_pk_mul_f32 v[50:51], v[32:33], v[48:49] op_sel_hi:[0,1]
	v_cvt_pk_bf16_f32 v49, v56, s0
	v_cvt_pk_bf16_f32 v48, v48, s0
	ds_write_b16 v99, v49 offset:6336
	ds_write_b16 v99, v48 offset:40128
	ds_read_u16 v158, v99 offset:4752
	ds_read_u16 v159, v99 offset:4224
	ds_read_u16 v160, v99 offset:38016
	ds_read_u16 v161, v99 offset:38544
	v_add_f32_e32 v49, v107, v33
	v_mul_f32_e32 v49, 0x3fb8aa3b, v49
	v_exp_f32_e32 v54, v49
	s_waitcnt lgkmcnt(11)
	v_lshlrev_b32_e32 v48, 16, v154
	v_mul_f32_e32 v48, 0x3d800000, v48
	v_cvt_pk_bf16_f32 v50, v50, v51
	v_mul_f32_e32 v48, v54, v48
	v_cvt_pk_bf16_f32 v48, v48, s0
	ds_write_b16 v99, v48 offset:5808
	v_add_f32_e32 v48, v108, v33
	v_mul_f32_e32 v48, 0x3fb8aa3b, v48
	v_rcp_f32_e32 v49, v54
	v_exp_f32_e32 v54, v48
	s_waitcnt lgkmcnt(11)
	v_lshlrev_b32_e32 v48, 16, v155
	v_mul_f32_e32 v55, 0x3d800000, v48
	v_rcp_f32_e32 v48, v54
	v_mul_f32_e32 v58, v54, v55
	s_waitcnt lgkmcnt(9)
	v_lshlrev_b32_e32 v55, 16, v157
	v_lshlrev_b32_e32 v54, 16, v156
	v_pk_mul_f32 v[48:49], v[48:49], v[54:55]
	v_cvt_pk_bf16_f32 v51, v52, v53
	v_cvt_pk_bf16_f32 v54, v49, s0
	ds_write_b16 v99, v54 offset:39600
	v_pk_mul_f32 v[54:55], v[32:33], v[48:49] op_sel_hi:[0,1]
	v_cvt_pk_bf16_f32 v49, v58, s0
	v_cvt_pk_bf16_f32 v48, v48, s0
	ds_write_b16 v99, v49 offset:5280
	ds_write_b16 v99, v48 offset:39072
	ds_read_u16 v154, v99 offset:3696
	ds_read_u16 v155, v99 offset:3168
	ds_read_u16 v156, v99 offset:36960
	ds_read_u16 v157, v99 offset:37488
	v_add_f32_e32 v49, v109, v33
	v_mul_f32_e32 v49, 0x3fb8aa3b, v49
	v_exp_f32_e32 v56, v49
	s_waitcnt lgkmcnt(11)
	v_lshlrev_b32_e32 v48, 16, v158
	v_mul_f32_e32 v48, 0x3d800000, v48
	v_mul_f32_e32 v48, v56, v48
	v_cvt_pk_bf16_f32 v48, v48, s0
	ds_write_b16 v99, v48 offset:4752
	v_add_f32_e32 v48, v111, v33
	v_mul_f32_e32 v48, 0x3fb8aa3b, v48
	v_rcp_f32_e32 v49, v56
	v_exp_f32_e32 v56, v48
	s_waitcnt lgkmcnt(11)
	v_lshlrev_b32_e32 v48, 16, v159
	v_mul_f32_e32 v57, 0x3d800000, v48
	v_rcp_f32_e32 v48, v56
	v_mul_f32_e32 v60, v56, v57
	s_waitcnt lgkmcnt(9)
	v_lshlrev_b32_e32 v57, 16, v161
	v_lshlrev_b32_e32 v56, 16, v160
	v_pk_mul_f32 v[48:49], v[48:49], v[56:57]
	s_nop 0
	v_cvt_pk_bf16_f32 v56, v49, s0
	ds_write_b16 v99, v56 offset:38544
	v_pk_mul_f32 v[56:57], v[32:33], v[48:49] op_sel_hi:[0,1]
	v_cvt_pk_bf16_f32 v49, v60, s0
	v_cvt_pk_bf16_f32 v48, v48, s0
	ds_write_b16 v99, v49 offset:4224
	ds_write_b16 v99, v48 offset:38016
	v_cvt_pk_bf16_f32 v48, v56, v57
	v_cvt_pk_bf16_f32 v49, v54, v55
	global_store_dwordx4 v[34:35], v[48:51], off offset:16
	ds_read_u16 v158, v99 offset:2640
	ds_read_u16 v159, v99 offset:2112
	ds_read_u16 v160, v99 offset:35904
	ds_read_u16 v161, v99 offset:36432
	v_add_f32_e32 v49, v110, v33
	v_mul_f32_e32 v49, 0x3fb8aa3b, v49
	v_exp_f32_e32 v50, v49
	s_waitcnt lgkmcnt(11)
	v_lshlrev_b32_e32 v48, 16, v154
	v_mul_f32_e32 v48, 0x3d800000, v48
	v_add_f32_e32 v55, v115, v33
	v_mul_f32_e32 v48, v50, v48
	v_cvt_pk_bf16_f32 v48, v48, s0
	ds_write_b16 v99, v48 offset:3696
	v_add_f32_e32 v48, v112, v33
	v_mul_f32_e32 v48, 0x3fb8aa3b, v48
	v_rcp_f32_e32 v49, v50
	v_exp_f32_e32 v50, v48
	s_waitcnt lgkmcnt(11)
	v_lshlrev_b32_e32 v48, 16, v155
	v_mul_f32_e32 v51, 0x3d800000, v48
	v_rcp_f32_e32 v48, v50
	s_waitcnt lgkmcnt(10)
	v_lshlrev_b32_e32 v52, 16, v156
	s_waitcnt lgkmcnt(9)
	v_lshlrev_b32_e32 v53, 16, v157
	v_mul_f32_e32 v50, v50, v51
	v_pk_mul_f32 v[48:49], v[48:49], v[52:53]
	v_cvt_pk_bf16_f32 v50, v50, s0
	v_cvt_pk_bf16_f32 v52, v49, s0
	ds_write_b16 v99, v52 offset:37488
	v_cvt_pk_bf16_f32 v52, v48, s0
	ds_write_b16 v99, v50 offset:3168
	ds_write_b16 v99, v52 offset:36960
	ds_read_u16 v154, v99 offset:1584
	ds_read_u16 v155, v99 offset:1056
	ds_read_u16 v156, v99 offset:34848
	ds_read_u16 v157, v99 offset:35376
	v_add_f32_e32 v51, v113, v33
	v_mul_f32_e32 v51, 0x3fb8aa3b, v51
	v_exp_f32_e32 v54, v51
	v_add_f32_e32 v51, v114, v33
	s_waitcnt lgkmcnt(11)
	v_lshlrev_b32_e32 v57, 16, v158
	v_mul_f32_e32 v51, 0x3fb8aa3b, v51
	v_mul_f32_e32 v57, 0x3d800000, v57
	v_exp_f32_e32 v56, v51
	v_rcp_f32_e32 v51, v54
	v_mul_f32_e32 v54, v54, v57
	v_cvt_pk_bf16_f32 v54, v54, s0
	ds_write_b16 v99, v54 offset:2640
	s_waitcnt lgkmcnt(11)
	v_lshlrev_b32_e32 v61, 16, v159
	v_rcp_f32_e32 v50, v56
	v_mul_f32_e32 v61, 0x3d800000, v61
	v_mul_f32_e32 v56, v56, v61
	v_cvt_pk_bf16_f32 v56, v56, s0
	ds_write_b16 v99, v56 offset:2112
	s_waitcnt lgkmcnt(10)
	v_lshlrev_b32_e32 v57, 16, v161
	v_lshlrev_b32_e32 v56, 16, v160
	v_pk_mul_f32 v[50:51], v[50:51], v[56:57]
	v_mul_f32_e32 v55, 0x3fb8aa3b, v55
	v_cvt_pk_bf16_f32 v54, v51, s0
	ds_write_b16 v99, v54 offset:36432
	v_cvt_pk_bf16_f32 v54, v50, s0
	ds_write_b16 v99, v54 offset:35904
	ds_read_u16 v158, v99 offset:528
	ds_read_u16 v159, v99 offset:0
	ds_read_u16 v160, v99 offset:33792
	ds_read_u16 v161, v99 offset:34320
	v_exp_f32_e32 v58, v55
	v_add_f32_e32 v55, v116, v33
	v_mul_f32_e32 v55, 0x3fb8aa3b, v55
	s_waitcnt lgkmcnt(11)
	v_lshlrev_b32_e32 v54, 16, v154
	v_mul_f32_e32 v54, 0x3d800000, v54
	v_mul_f32_e32 v54, v58, v54
	v_exp_f32_e32 v59, v55
	v_cvt_pk_bf16_f32 v54, v54, s0
	ds_write_b16 v99, v54 offset:1584
	s_waitcnt lgkmcnt(11)
	v_lshlrev_b32_e32 v56, 16, v155
	v_rcp_f32_e32 v53, v58
	v_rcp_f32_e32 v52, v59
	v_mul_f32_e32 v56, 0x3d800000, v56
	v_mul_f32_e32 v56, v59, v56
	v_cvt_pk_bf16_f32 v56, v56, s0
	ds_write_b16 v99, v56 offset:1056
	s_waitcnt lgkmcnt(10)
	v_lshlrev_b32_e32 v57, 16, v157
	v_lshlrev_b32_e32 v56, 16, v156
	v_pk_mul_f32 v[52:53], v[52:53], v[56:57]
	v_add_f32_e32 v55, v117, v33
	v_cvt_pk_bf16_f32 v54, v53, s0
	ds_write_b16 v99, v54 offset:35376
	v_cvt_pk_bf16_f32 v54, v52, s0
	ds_write_b16 v99, v54 offset:34848
	v_add_f32_e32 v33, v100, v33
	v_mul_f32_e32 v33, 0x3fb8aa3b, v33
	v_exp_f32_e32 v33, v33
	v_mul_f32_e32 v55, 0x3fb8aa3b, v55
	v_exp_f32_e32 v60, v55
	v_add_u32_e32 v114, v88, v47
	v_pk_mul_f32 v[56:57], v[32:33], v[48:49] op_sel_hi:[0,1]
	s_waitcnt lgkmcnt(7)
	v_lshlrev_b32_e32 v49, 16, v158
	v_mul_f32_e32 v49, 0x3d800000, v49
	v_mul_f32_e32 v49, v60, v49
	v_cvt_pk_bf16_f32 v49, v49, s0
	ds_write_b16 v99, v49 offset:528
	v_rcp_f32_e32 v55, v60
	v_rcp_f32_e32 v54, v33
	s_waitcnt lgkmcnt(7)
	v_lshlrev_b32_e32 v48, 16, v159
	v_mul_f32_e32 v48, 0x3d800000, v48
	v_pk_mul_f32 v[50:51], v[32:33], v[50:51] op_sel_hi:[0,1]
	v_mul_f32_e32 v33, v33, v48
	s_waitcnt lgkmcnt(5)
	v_lshlrev_b32_e32 v49, 16, v161
	v_lshlrev_b32_e32 v48, 16, v160
	v_cvt_pk_bf16_f32 v33, v33, s0
	v_pk_mul_f32 v[48:49], v[54:55], v[48:49]
	ds_write_b16 v99, v33
	v_pk_mul_f32 v[52:53], v[32:33], v[52:53] op_sel_hi:[0,1]
	v_cvt_pk_bf16_f32 v33, v49, s0
	ds_write_b16 v99, v33 offset:34320
	v_cvt_pk_bf16_f32 v33, v48, s0
	ds_write_b16 v99, v33 offset:33792
	v_pk_mul_f32 v[32:33], v[32:33], v[48:49] op_sel_hi:[0,1]
	v_cvt_pk_bf16_f32 v48, v32, v33
	v_cvt_pk_bf16_f32 v49, v52, v53
	v_cvt_pk_bf16_f32 v50, v50, v51
	v_cvt_pk_bf16_f32 v51, v56, v57
	global_store_dwordx4 v[34:35], v[48:51], off
	s_waitcnt lgkmcnt(0)
	s_barrier
	ds_read_b128 v[32:35], v86
	ds_read_b128 v[48:51], v114 offset:33792
	ds_read_b128 v[52:55], v86 offset:64
	ds_read_b128 v[56:59], v114 offset:33856
	ds_read_b128 v[60:63], v86 offset:128
	s_waitcnt lgkmcnt(3)
	v_mfma_f32_16x16x32_bf16 v[48:51], v[32:35], v[48:51], 0
	v_cndmask_b32_e64 v47, v64, 0, s[4:5]
	ds_read_b128 v[64:67], v114 offset:33920
	ds_read_b128 v[68:71], v86 offset:192
	s_add_u32 s0, s1, s0
	s_waitcnt lgkmcnt(3)
	v_mfma_f32_16x16x32_bf16 v[48:51], v[52:55], v[56:59], v[48:51]
	ds_read_b128 v[56:59], v114 offset:33984
	ds_read_b128 v[82:85], v86 offset:256
	ds_read_b128 v[88:91], v114 offset:34112
	s_addc_u32 s1, s6, 0
	s_waitcnt lgkmcnt(4)
	v_mfma_f32_16x16x32_bf16 v[48:51], v[60:63], v[64:67], v[48:51]
	ds_read_b128 v[64:67], v114 offset:34048
	v_lshl_add_u64 v[78:79], s[0:1], 0, v[78:79]
	v_lshl_add_u64 v[78:79], v[78:79], 0, v[96:97]
	s_waitcnt lgkmcnt(3)
	v_mfma_f32_16x16x32_bf16 v[48:51], v[68:71], v[56:59], v[48:51]
	ds_read_b128 v[56:59], v86 offset:320
	v_lshl_add_u64 v[74:75], s[0:1], 0, v[74:75]
	v_lshl_add_u64 v[72:73], s[0:1], 0, v[72:73]
	s_waitcnt lgkmcnt(1)
	v_mfma_f32_16x16x32_bf16 v[48:51], v[82:85], v[64:67], v[48:51]
	ds_read_b128 v[64:67], v86 offset:384
	ds_read_b128 v[98:101], v94
	ds_read_b128 v[102:105], v95
	ds_read_b128 v[106:109], v114 offset:34176
	ds_read_b128 v[110:113], v86 offset:448
	v_lshl_add_u64 v[74:75], v[74:75], 0, v[96:97]
	s_waitcnt lgkmcnt(3)
	global_store_dwordx4 v[78:79], v[98:101], off
	v_mfma_f32_16x16x32_bf16 v[48:51], v[56:59], v[88:91], v[48:51]
	v_lshl_add_u64 v[88:89], s[0:1], 0, v[76:77]
	v_lshl_add_u64 v[88:89], v[88:89], 0, v[96:97]
	ds_read_b128 v[76:79], v114 offset:34240
	ds_read_b128 v[98:101], v114 offset:42304
	s_waitcnt lgkmcnt(4)
	global_store_dwordx4 v[88:89], v[102:105], off
	ds_read_b128 v[88:91], v114 offset:42240
	s_waitcnt lgkmcnt(4)
	v_mfma_f32_16x16x32_bf16 v[48:51], v[64:67], v[106:109], v[48:51]
	v_cmp_ge_u32_e64 s[6:7], v87, v36
	s_waitcnt lgkmcnt(2)
	v_mfma_f32_16x16x32_bf16 v[48:51], v[110:113], v[76:79], v[48:51]
	ds_read_b128 v[76:79], v93
	s_waitcnt lgkmcnt(1)
	v_mfma_f32_16x16x32_bf16 v[32:35], v[32:35], v[88:91], 0
	ds_read_b128 v[88:91], v92
	ds_read_b128 v[92:95], v114 offset:42368
	s_waitcnt lgkmcnt(2)
	global_store_dwordx4 v[74:75], v[76:79], off
	s_nop 0
	v_cndmask_b32_e64 v48, 0, v48, s[6:7]
	v_mfma_f32_16x16x32_bf16 v[32:35], v[52:55], v[98:101], v[32:35]
	ds_read_b128 v[52:55], v114 offset:42432
	s_waitcnt lgkmcnt(1)
	v_mfma_f32_16x16x32_bf16 v[32:35], v[60:63], v[92:95], v[32:35]
	v_lshl_add_u64 v[60:61], v[72:73], 0, v[96:97]
	global_store_dwordx4 v[60:61], v[88:91], off
	ds_read_b128 v[60:63], v114 offset:42496
	s_waitcnt lgkmcnt(1)
	v_mfma_f32_16x16x32_bf16 v[32:35], v[68:71], v[52:55], v[32:35]
	ds_read_b128 v[52:55], v114 offset:42560
	s_waitcnt lgkmcnt(1)
	v_mfma_f32_16x16x32_bf16 v[32:35], v[82:85], v[60:63], v[32:35]
	v_add_f32_e32 v60, v47, v48
	v_cndmask_b32_e64 v47, 0, v49, s[4:5]
	v_add_f32_e32 v61, v46, v47
	ds_read_b128 v[46:49], v114 offset:42624
	s_waitcnt lgkmcnt(1)
	v_mfma_f32_16x16x32_bf16 v[32:35], v[56:59], v[52:55], v[32:35]
	ds_read_b128 v[52:55], v114 offset:42688
	v_cmp_ge_u32_e64 s[4:5], v87, v40
	s_waitcnt lgkmcnt(0)
	v_mfma_f32_16x16x32_bf16 v[32:35], v[64:67], v[46:49], v[32:35]
	v_cndmask_b32_e64 v50, 0, v50, s[4:5]
	v_cmp_ge_u32_e64 s[4:5], v87, v38
	v_add_f32_e32 v45, v45, v50
	v_mfma_f32_16x16x32_bf16 v[32:35], v[110:113], v[52:55], v[32:35]
	v_cndmask_b32_e64 v46, 0, v51, s[4:5]
	v_cmp_ge_u32_e64 s[4:5], v37, v36
	v_mul_lo_u32 v36, v36, s89
	s_barrier
	s_nop 3
	v_cndmask_b32_e64 v32, 0, v32, s[4:5]
	v_cndmask_b32_e32 v33, 0, v33, vcc
	v_cmp_ge_u32_e32 vcc, v37, v40
	v_add_f32_e32 v32, v43, v32
	v_add_f32_e32 v33, v42, v33
	v_cndmask_b32_e32 v34, 0, v34, vcc
	v_cmp_ge_u32_e32 vcc, v37, v38
	v_lshlrev_b32_e32 v37, 1, v81
	v_cvt_pk_bf16_f32 v38, v60, s0
	v_readlane_b32 s0, v253, 19
	v_add_f32_e32 v34, v41, v34
	v_cndmask_b32_e32 v35, 0, v35, vcc
	v_add3_u32 v36, s0, v37, v36
	v_cvt_pk_bf16_f32 v32, v32, s0
	v_cvt_pk_bf16_f32 v37, v61, s0
	ds_write_b16 v36, v32 offset:32
	v_cvt_pk_bf16_f32 v32, v33, s0
	v_add_f32_e32 v44, v44, v46
	v_add_f32_e32 v35, v39, v35
	ds_write_b16 v36, v37 offset:144
	v_cvt_pk_bf16_f32 v37, v45, s0
	ds_write_b16 v36, v32 offset:176
	v_cvt_pk_bf16_f32 v32, v34, s0
	ds_write_b16 v36, v37 offset:288
	v_cvt_pk_bf16_f32 v37, v44, s0
	ds_write_b16 v36, v32 offset:320
	v_cvt_pk_bf16_f32 v32, v35, s0
	s_lshl_b32 s0, s56, 1
	s_add_u32 s0, s53, s0
	ds_write_b16 v36, v32 offset:464
	s_addc_u32 s1, s54, 0
	v_mul_u32_u24_e32 v32, 0x90, v81
	s_add_i32 s4, 0, 0x10800
	v_lshlrev_b32_e32 v33, 1, v80
	v_add3_u32 v72, s4, v32, v33
	ds_write_b16 v36, v38
	ds_write_b16 v36, v37 offset:432
	s_waitcnt lgkmcnt(0)
	s_barrier
	ds_read_b128 v[32:35], v72
	ds_read_b128 v[36:39], v72 offset:64
	ds_read_b128 v[44:47], v72 offset:2304
	ds_read_b128 v[48:51], v72 offset:2368
	s_waitcnt lgkmcnt(1)
	v_mfma_f32_16x16x32_bf16 v[52:55], v[28:31], v[44:47], 0
	ds_read_b128 v[56:59], v72 offset:4608
	ds_read_b128 v[60:63], v72 offset:4672
	ds_read_b128 v[68:71], v72 offset:6912
	ds_read_b128 v[72:75], v72 offset:6976
	v_or_b32_e32 v82, s12, v81
	v_mfma_f32_16x16x32_bf16 v[40:43], v[28:31], v[32:35], 0
	v_mov_b32_e32 v81, v97
	v_lshl_add_u64 v[80:81], s[0:1], 0, v[80:81]
	v_ashrrev_i32_e32 v83, 31, v82
	s_waitcnt lgkmcnt(4)
	v_mfma_f32_16x16x32_bf16 v[52:55], v[24:27], v[48:51], v[52:55]
	v_lshl_add_u64 v[80:81], s[84:85], 1, v[80:81]
	v_lshlrev_b64 v[86:87], 12, v[82:83]
	v_lshl_add_u64 v[86:87], v[80:81], 0, v[86:87]
	v_mfma_f32_16x16x32_bf16 v[40:43], v[24:27], v[36:39], v[40:43]
	v_readlane_b32 s0, v254, 32
	s_nop 2
	v_cvt_pk_bf16_f32 v52, v52, v53
	v_cvt_pk_bf16_f32 v53, v54, v55
	s_waitcnt lgkmcnt(3)
	v_mfma_f32_16x16x32_bf16 v[64:67], v[28:31], v[56:59], 0
	v_or_b32_e32 v54, 16, v82
	v_ashrrev_i32_e32 v55, 31, v54
	v_cvt_pk_bf16_f32 v84, v40, v41
	s_waitcnt lgkmcnt(2)
	v_mfma_f32_16x16x32_bf16 v[64:67], v[24:27], v[60:63], v[64:67]
	v_cvt_pk_bf16_f32 v85, v42, v43
	v_lshlrev_b64 v[54:55], 12, v[54:55]
	global_store_dwordx2 v[86:87], v[84:85], off
	s_waitcnt lgkmcnt(1)
	v_mfma_f32_16x16x32_bf16 v[28:31], v[28:31], v[68:71], 0
	v_lshl_add_u64 v[84:85], v[80:81], 0, v[54:55]
	v_or_b32_e32 v54, 32, v82
	v_ashrrev_i32_e32 v55, 31, v54
	v_lshlrev_b64 v[54:55], 12, v[54:55]
	global_store_dwordx2 v[84:85], v[52:53], off
	v_cvt_pk_bf16_f32 v52, v64, v65
	v_cvt_pk_bf16_f32 v53, v66, v67
	v_lshl_add_u64 v[64:65], v[80:81], 0, v[54:55]
	s_waitcnt lgkmcnt(0)
	v_mfma_f32_16x16x32_bf16 v[24:27], v[24:27], v[72:75], v[28:31]
	global_store_dwordx2 v[64:65], v[52:53], off
	v_or_b32_e32 v82, 48, v82
	v_ashrrev_i32_e32 v83, 31, v82
	v_mfma_f32_16x16x32_bf16 v[28:31], v[20:23], v[32:35], 0
	s_add_i32 s16, s16, s34
	s_nop 2
	v_cvt_pk_bf16_f32 v66, v24, v25
	v_cvt_pk_bf16_f32 v67, v26, v27
	v_mfma_f32_16x16x32_bf16 v[76:79], v[20:23], v[44:47], 0
	s_add_i32 s55, s55, s86
	s_add_i32 s10, s10, s0
	s_cmpk_gt_i32 s16, 0x2ff
	v_mfma_f32_16x16x32_bf16 v[40:43], v[20:23], v[56:59], 0
	v_mfma_f32_16x16x32_bf16 v[20:23], v[20:23], v[68:71], 0
	v_mfma_f32_16x16x32_bf16 v[52:55], v[12:15], v[44:47], 0
	v_mfma_f32_16x16x32_bf16 v[28:31], v[16:19], v[36:39], v[28:31]
	v_mfma_f32_16x16x32_bf16 v[76:79], v[16:19], v[48:51], v[76:79]
	v_mfma_f32_16x16x32_bf16 v[40:43], v[16:19], v[60:63], v[40:43]
	s_nop 5
	v_cvt_pk_bf16_f32 v28, v28, v29
	v_cvt_pk_bf16_f32 v29, v30, v31
	global_store_dwordx2 v[86:87], v[28:29], off offset:32
	v_mfma_f32_16x16x32_bf16 v[16:19], v[16:19], v[72:75], v[20:23]
	v_mfma_f32_16x16x32_bf16 v[20:23], v[12:15], v[32:35], 0
	v_cvt_pk_bf16_f32 v40, v40, v41
	v_cvt_pk_bf16_f32 v41, v42, v43
	global_store_dwordx2 v[64:65], v[40:41], off offset:32
	v_mfma_f32_16x16x32_bf16 v[24:27], v[8:11], v[48:51], v[52:55]
	s_nop 2
	v_lshlrev_b64 v[52:53], 12, v[82:83]
	v_lshl_add_u64 v[80:81], v[80:81], 0, v[52:53]
	v_mfma_f32_16x16x32_bf16 v[52:55], v[12:15], v[56:59], 0
	global_store_dwordx2 v[80:81], v[66:67], off
	v_mfma_f32_16x16x32_bf16 v[12:15], v[12:15], v[68:71], 0
	v_mfma_f32_16x16x32_bf16 v[20:23], v[8:11], v[36:39], v[20:23]
	v_mfma_f32_16x16x32_bf16 v[28:31], v[8:11], v[60:63], v[52:55]
	v_mfma_f32_16x16x32_bf16 v[8:11], v[8:11], v[72:75], v[12:15]
	s_nop 2
	v_cvt_pk_bf16_f32 v52, v76, v77
	v_cvt_pk_bf16_f32 v53, v78, v79
	global_store_dwordx2 v[84:85], v[52:53], off offset:32
	v_cvt_pk_bf16_f32 v12, v16, v17
	v_cvt_pk_bf16_f32 v13, v18, v19
	v_cvt_pk_bf16_f32 v16, v20, v21
	v_cvt_pk_bf16_f32 v17, v22, v23
	global_store_dwordx2 v[80:81], v[12:13], off offset:32
	v_mfma_f32_16x16x32_bf16 v[12:15], v[4:7], v[32:35], 0
	global_store_dwordx2 v[86:87], v[16:17], off offset:64
	v_cvt_pk_bf16_f32 v16, v24, v25
	v_cvt_pk_bf16_f32 v17, v26, v27
	v_cvt_pk_bf16_f32 v8, v8, v9
	v_cvt_pk_bf16_f32 v9, v10, v11
	global_store_dwordx2 v[84:85], v[16:17], off offset:64
	v_mfma_f32_16x16x32_bf16 v[16:19], v[4:7], v[44:47], 0
	global_store_dwordx2 v[80:81], v[8:9], off offset:64
	v_cvt_pk_bf16_f32 v20, v28, v29
	v_cvt_pk_bf16_f32 v21, v30, v31
	v_mfma_f32_16x16x32_bf16 v[8:11], v[4:7], v[56:59], 0
	global_store_dwordx2 v[64:65], v[20:21], off offset:64
	v_mfma_f32_16x16x32_bf16 v[4:7], v[4:7], v[68:71], 0
	v_mfma_f32_16x16x32_bf16 v[12:15], v[0:3], v[36:39], v[12:15]
	v_mfma_f32_16x16x32_bf16 v[16:19], v[0:3], v[48:51], v[16:19]
	v_mfma_f32_16x16x32_bf16 v[8:11], v[0:3], v[60:63], v[8:11]
	s_nop 5
	v_cvt_pk_bf16_f32 v12, v12, v13
	v_cvt_pk_bf16_f32 v13, v14, v15
	global_store_dwordx2 v[86:87], v[12:13], off offset:96
	v_mfma_f32_16x16x32_bf16 v[0:3], v[0:3], v[72:75], v[4:7]
	v_cvt_pk_bf16_f32 v12, v16, v17
	v_cvt_pk_bf16_f32 v13, v18, v19
	v_cvt_pk_bf16_f32 v8, v8, v9
	v_cvt_pk_bf16_f32 v9, v10, v11
	global_store_dwordx2 v[84:85], v[12:13], off offset:96
	s_nop 2
	v_cvt_pk_bf16_f32 v0, v0, v1
	v_cvt_pk_bf16_f32 v1, v2, v3
	global_store_dwordx2 v[64:65], v[8:9], off offset:96
	global_store_dwordx2 v[80:81], v[0:1], off offset:96
	s_barrier
	s_cbranch_scc1 .LBB0_423

.LBB0_421:
	s_or_b64 exec, exec, s[4:5]
	v_mul_i32_i24_e32 v67, 0x2100, v101
	v_lshlrev_b32_e32 v67, 1, v67
	v_lshlrev_b32_sdwa v69, v250, v66 dst_sel:DWORD dst_unused:UNUSED_PAD src0_sel:DWORD src1_sel:BYTE_0
	v_add3_u32 v99, 0, v67, v69
	s_barrier
	s_waitcnt lgkmcnt(0)
	v_add_f32_e32 v69, v71, v68
	ds_read_u16 v154, v99 offset:0
	ds_read_u16 v155, v99 offset:528
	ds_read_u16 v156, v99 offset:33792
	ds_read_u16 v157, v99 offset:34320
	ds_read_u16 v158, v99 offset:1056
	ds_read_u16 v159, v99 offset:1584
	ds_read_u16 v160, v99 offset:34848
	ds_read_u16 v161, v99 offset:35376
	v_mul_f32_e32 v69, 0x3fb8aa3b, v69
	v_exp_f32_e32 v69, v69
	s_lshl_b64 s[4:5], s[10:11], 15
	s_add_u32 s4, s43, s4
	s_waitcnt lgkmcnt(7)
	v_lshlrev_b32_e32 v71, 16, v154
	v_mul_f32_e32 v71, 0x3d800000, v71
	v_rcp_f32_e32 v144, v69
	v_mul_f32_e32 v69, v69, v71
	v_cvt_pk_bf16_f32 v69, v69, s0
	ds_write_b16 v99, v69
	v_add_f32_e32 v69, v70, v68
	v_mul_f32_e32 v69, 0x3fb8aa3b, v69
	v_exp_f32_e32 v69, v69
	v_mov_b32_e32 v67, 7
	v_lshlrev_b32_e32 v82, 5, v101
	s_waitcnt lgkmcnt(7)
	v_lshlrev_b32_e32 v70, 16, v155
	v_mul_f32_e32 v70, 0x3d800000, v70
	v_rcp_f32_e32 v145, v69
	v_mul_f32_e32 v69, v69, v70
	v_cvt_pk_bf16_f32 v69, v69, s0
	ds_write_b16 v99, v69 offset:528
	s_addc_u32 s5, s44, s5
	s_waitcnt lgkmcnt(7)
	v_lshlrev_b32_e32 v70, 16, v156
	s_waitcnt lgkmcnt(6)
	v_lshlrev_b32_e32 v71, 16, v157
	v_pk_mul_f32 v[144:145], v[144:145], v[70:71]
	v_lshlrev_b32_sdwa v84, v67, v66 dst_sel:DWORD dst_unused:UNUSED_PAD src0_sel:DWORD src1_sel:BYTE_0
	v_pk_mul_f32 v[70:71], v[64:65], v[144:145] op_sel_hi:[0,1]
	v_cvt_pk_bf16_f32 v144, v144, s0
	v_cvt_pk_bf16_f32 v69, v145, s0
	ds_write_b16 v99, v144 offset:33792
	ds_write_b16 v99, v69 offset:34320
	v_add_f32_e32 v69, v87, v68
	ds_read_u16 v154, v99 offset:2112
	ds_read_u16 v155, v99 offset:2640
	ds_read_u16 v156, v99 offset:35904
	ds_read_u16 v157, v99 offset:36432
	v_mul_f32_e32 v69, 0x3fb8aa3b, v69
	v_exp_f32_e32 v69, v69
	v_mov_b32_e32 v85, v97
	v_lshl_add_u64 v[66:67], s[4:5], 0, v[84:85]
	s_waitcnt lgkmcnt(11)
	v_lshlrev_b32_e32 v87, 16, v158
	v_mul_f32_e32 v87, 0x3d800000, v87
	v_rcp_f32_e32 v144, v69
	v_mul_f32_e32 v69, v69, v87
	v_cvt_pk_bf16_f32 v69, v69, s0
	ds_write_b16 v99, v69 offset:1056
	v_add_f32_e32 v69, v86, v68
	v_mul_f32_e32 v69, 0x3fb8aa3b, v69
	v_exp_f32_e32 v69, v69
	v_ashrrev_i32_e32 v83, 31, v82
	v_lshl_add_u64 v[66:67], v[82:83], 1, v[66:67]
	s_waitcnt lgkmcnt(11)
	v_lshlrev_b32_e32 v86, 16, v159
	v_mul_f32_e32 v86, 0x3d800000, v86
	v_rcp_f32_e32 v145, v69
	v_mul_f32_e32 v69, v69, v86
	v_cvt_pk_bf16_f32 v69, v69, s0
	ds_write_b16 v99, v69 offset:1584
	s_add_u32 s1, s45, s6
	s_waitcnt lgkmcnt(11)
	v_lshlrev_b32_e32 v86, 16, v160
	s_waitcnt lgkmcnt(10)
	v_lshlrev_b32_e32 v87, 16, v161
	v_pk_mul_f32 v[144:145], v[144:145], v[86:87]
	s_addc_u32 s5, s48, s7
	v_pk_mul_f32 v[86:87], v[64:65], v[144:145] op_sel_hi:[0,1]
	v_cvt_pk_bf16_f32 v144, v144, s0
	v_cvt_pk_bf16_f32 v69, v145, s0
	ds_write_b16 v99, v144 offset:34848
	ds_write_b16 v99, v69 offset:35376
	v_add_f32_e32 v69, v143, v68
	ds_read_u16 v158, v99 offset:3168
	ds_read_u16 v159, v99 offset:3696
	ds_read_u16 v160, v99 offset:36960
	ds_read_u16 v161, v99 offset:37488
	v_mul_f32_e32 v69, 0x3fb8aa3b, v69
	v_exp_f32_e32 v69, v69
	v_lshlrev_b32_e32 v80, 3, v98
	s_waitcnt lgkmcnt(11)
	v_lshlrev_b32_e32 v143, 16, v154
	v_mul_f32_e32 v143, 0x3d800000, v143
	v_rcp_f32_e32 v144, v69
	v_mul_f32_e32 v69, v69, v143
	v_cvt_pk_bf16_f32 v69, v69, s0
	ds_write_b16 v99, v69 offset:2112
	v_add_f32_e32 v69, v142, v68
	v_mul_f32_e32 v69, 0x3fb8aa3b, v69
	v_exp_f32_e32 v69, v69
	s_waitcnt lgkmcnt(11)
	v_lshlrev_b32_e32 v142, 16, v155
	v_mul_f32_e32 v142, 0x3d800000, v142
	v_rcp_f32_e32 v145, v69
	v_mul_f32_e32 v69, v69, v142
	v_cvt_pk_bf16_f32 v69, v69, s0
	ds_write_b16 v99, v69 offset:2640
	s_waitcnt lgkmcnt(11)
	v_lshlrev_b32_e32 v142, 16, v156
	s_waitcnt lgkmcnt(10)
	v_lshlrev_b32_e32 v143, 16, v157
	v_pk_mul_f32 v[142:143], v[144:145], v[142:143]
	s_nop 0
	v_pk_mul_f32 v[144:145], v[64:65], v[142:143] op_sel_hi:[0,1]
	v_cvt_pk_bf16_f32 v142, v142, s0
	v_cvt_pk_bf16_f32 v69, v143, s0
	ds_write_b16 v99, v142 offset:35904
	ds_write_b16 v99, v69 offset:36432
	v_add_f32_e32 v69, v141, v68
	ds_read_u16 v154, v99 offset:4224
	ds_read_u16 v155, v99 offset:4752
	ds_read_u16 v156, v99 offset:38016
	ds_read_u16 v157, v99 offset:38544
	v_mul_f32_e32 v69, 0x3fb8aa3b, v69
	v_exp_f32_e32 v69, v69
	s_waitcnt lgkmcnt(11)
	v_lshlrev_b32_e32 v141, 16, v158
	v_mul_f32_e32 v141, 0x3d800000, v141
	v_rcp_f32_e32 v142, v69
	v_mul_f32_e32 v69, v69, v141
	v_cvt_pk_bf16_f32 v69, v69, s0
	ds_write_b16 v99, v69 offset:3168
	v_add_f32_e32 v69, v140, v68
	v_mul_f32_e32 v69, 0x3fb8aa3b, v69
	v_exp_f32_e32 v69, v69
	s_waitcnt lgkmcnt(11)
	v_lshlrev_b32_e32 v140, 16, v159
	v_mul_f32_e32 v140, 0x3d800000, v140
	v_rcp_f32_e32 v143, v69
	v_mul_f32_e32 v69, v69, v140
	v_cvt_pk_bf16_f32 v69, v69, s0
	ds_write_b16 v99, v69 offset:3696
	s_waitcnt lgkmcnt(11)
	v_lshlrev_b32_e32 v140, 16, v160
	s_waitcnt lgkmcnt(10)
	v_lshlrev_b32_e32 v141, 16, v161
	v_pk_mul_f32 v[140:141], v[142:143], v[140:141]
	v_cvt_pk_bf16_f32 v142, v144, v145
	v_pk_mul_f32 v[146:147], v[64:65], v[140:141] op_sel_hi:[0,1]
	v_cvt_pk_bf16_f32 v140, v140, s0
	v_cvt_pk_bf16_f32 v69, v141, s0
	ds_write_b16 v99, v140 offset:36960
	ds_write_b16 v99, v69 offset:37488
	v_cvt_pk_bf16_f32 v140, v70, v71
	v_cvt_pk_bf16_f32 v141, v86, v87
	v_cvt_pk_bf16_f32 v143, v146, v147
	global_store_dwordx4 v[66:67], v[140:143], off
	ds_read_u16 v158, v99 offset:5280
	ds_read_u16 v159, v99 offset:5808
	ds_read_u16 v160, v99 offset:39072
	ds_read_u16 v161, v99 offset:39600
	v_add_f32_e32 v69, v139, v68
	v_mul_f32_e32 v69, 0x3fb8aa3b, v69
	v_exp_f32_e32 v69, v69
	s_waitcnt lgkmcnt(11)
	v_lshlrev_b32_e32 v70, 16, v154
	v_mul_f32_e32 v71, 0x3d800000, v70
	v_rcp_f32_e32 v70, v69
	v_mul_f32_e32 v69, v69, v71
	v_cvt_pk_bf16_f32 v69, v69, s0
	ds_write_b16 v99, v69 offset:4224
	v_add_f32_e32 v69, v138, v68
	v_mul_f32_e32 v69, 0x3fb8aa3b, v69
	v_exp_f32_e32 v69, v69
	s_waitcnt lgkmcnt(11)
	v_lshlrev_b32_e32 v71, 16, v155
	v_mul_f32_e32 v86, 0x3d800000, v71
	v_rcp_f32_e32 v71, v69
	v_mul_f32_e32 v69, v69, v86
	v_cvt_pk_bf16_f32 v69, v69, s0
	ds_write_b16 v99, v69 offset:4752
	s_waitcnt lgkmcnt(11)
	v_lshlrev_b32_e32 v86, 16, v156
	s_waitcnt lgkmcnt(10)
	v_lshlrev_b32_e32 v87, 16, v157
	v_pk_mul_f32 v[86:87], v[70:71], v[86:87]
	s_nop 0
	v_pk_mul_f32 v[70:71], v[64:65], v[86:87] op_sel_hi:[0,1]
	v_cvt_pk_bf16_f32 v86, v86, s0
	v_cvt_pk_bf16_f32 v69, v87, s0
	ds_write_b16 v99, v86 offset:38016
	ds_write_b16 v99, v69 offset:38544
	ds_read_u16 v154, v99 offset:6336
	ds_read_u16 v155, v99 offset:6864
	ds_read_u16 v156, v99 offset:40128
	ds_read_u16 v157, v99 offset:40656
	v_add_f32_e32 v69, v137, v68
	v_mul_f32_e32 v69, 0x3fb8aa3b, v69
	v_exp_f32_e32 v69, v69
	s_waitcnt lgkmcnt(11)
	v_lshlrev_b32_e32 v86, 16, v158
	v_mul_f32_e32 v87, 0x3d800000, v86
	v_rcp_f32_e32 v86, v69
	v_mul_f32_e32 v69, v69, v87
	v_cvt_pk_bf16_f32 v69, v69, s0
	ds_write_b16 v99, v69 offset:5280
	v_add_f32_e32 v69, v136, v68
	v_mul_f32_e32 v69, 0x3fb8aa3b, v69
	v_exp_f32_e32 v69, v69
	s_waitcnt lgkmcnt(11)
	v_lshlrev_b32_e32 v87, 16, v159
	v_mul_f32_e32 v136, 0x3d800000, v87
	v_rcp_f32_e32 v87, v69
	v_mul_f32_e32 v69, v69, v136
	v_cvt_pk_bf16_f32 v69, v69, s0
	ds_write_b16 v99, v69 offset:5808
	s_waitcnt lgkmcnt(11)
	v_lshlrev_b32_e32 v136, 16, v160
	s_waitcnt lgkmcnt(10)
	v_lshlrev_b32_e32 v137, 16, v161
	v_pk_mul_f32 v[136:137], v[86:87], v[136:137]
	s_nop 0
	v_pk_mul_f32 v[86:87], v[64:65], v[136:137] op_sel_hi:[0,1]
	v_cvt_pk_bf16_f32 v136, v136, s0
	v_cvt_pk_bf16_f32 v69, v137, s0
	ds_write_b16 v99, v136 offset:39072
	ds_write_b16 v99, v69 offset:39600
	v_add_f32_e32 v69, v135, v68
	ds_read_u16 v158, v99 offset:7392
	ds_read_u16 v159, v99 offset:7920
	ds_read_u16 v160, v99 offset:41184
	ds_read_u16 v161, v99 offset:41712
	v_mul_f32_e32 v69, 0x3fb8aa3b, v69
	v_exp_f32_e32 v69, v69
	s_waitcnt lgkmcnt(11)
	v_lshlrev_b32_e32 v135, 16, v154
	v_mul_f32_e32 v135, 0x3d800000, v135
	v_rcp_f32_e32 v136, v69
	v_mul_f32_e32 v69, v69, v135
	v_cvt_pk_bf16_f32 v69, v69, s0
	ds_write_b16 v99, v69 offset:6336
	v_add_f32_e32 v69, v134, v68
	v_mul_f32_e32 v69, 0x3fb8aa3b, v69
	v_exp_f32_e32 v69, v69
	s_waitcnt lgkmcnt(11)
	v_lshlrev_b32_e32 v134, 16, v155
	v_mul_f32_e32 v134, 0x3d800000, v134
	v_rcp_f32_e32 v137, v69
	v_mul_f32_e32 v69, v69, v134
	v_cvt_pk_bf16_f32 v69, v69, s0
	ds_write_b16 v99, v69 offset:6864
	s_waitcnt lgkmcnt(11)
	v_lshlrev_b32_e32 v134, 16, v156
	s_waitcnt lgkmcnt(10)
	v_lshlrev_b32_e32 v135, 16, v157
	v_pk_mul_f32 v[134:135], v[136:137], v[134:135]
	s_nop 0
	v_pk_mul_f32 v[136:137], v[64:65], v[134:135] op_sel_hi:[0,1]
	v_cvt_pk_bf16_f32 v134, v134, s0
	v_cvt_pk_bf16_f32 v69, v135, s0
	ds_write_b16 v99, v134 offset:40128
	ds_write_b16 v99, v69 offset:40656
	v_add_f32_e32 v69, v133, v68
	ds_read_u16 v154, v99 offset:8448
	ds_read_u16 v155, v99 offset:8976
	ds_read_u16 v156, v99 offset:42240
	ds_read_u16 v157, v99 offset:42768
	v_mul_f32_e32 v69, 0x3fb8aa3b, v69
	v_exp_f32_e32 v69, v69
	s_waitcnt lgkmcnt(11)
	v_lshlrev_b32_e32 v133, 16, v158
	v_mul_f32_e32 v133, 0x3d800000, v133
	v_rcp_f32_e32 v134, v69
	v_mul_f32_e32 v69, v69, v133
	v_cvt_pk_bf16_f32 v69, v69, s0
	ds_write_b16 v99, v69 offset:7392
	v_add_f32_e32 v69, v132, v68
	v_mul_f32_e32 v69, 0x3fb8aa3b, v69
	v_exp_f32_e32 v69, v69
	s_waitcnt lgkmcnt(11)
	v_lshlrev_b32_e32 v132, 16, v159
	v_mul_f32_e32 v132, 0x3d800000, v132
	v_rcp_f32_e32 v135, v69
	v_mul_f32_e32 v69, v69, v132
	v_cvt_pk_bf16_f32 v69, v69, s0
	ds_write_b16 v99, v69 offset:7920
	s_waitcnt lgkmcnt(11)
	v_lshlrev_b32_e32 v132, 16, v160
	s_waitcnt lgkmcnt(10)
	v_lshlrev_b32_e32 v133, 16, v161
	v_pk_mul_f32 v[132:133], v[134:135], v[132:133]
	v_cvt_pk_bf16_f32 v134, v136, v137
	v_pk_mul_f32 v[138:139], v[64:65], v[132:133] op_sel_hi:[0,1]
	v_cvt_pk_bf16_f32 v132, v132, s0
	v_cvt_pk_bf16_f32 v69, v133, s0
	ds_write_b16 v99, v132 offset:41184
	ds_write_b16 v99, v69 offset:41712
	v_cvt_pk_bf16_f32 v132, v70, v71
	v_cvt_pk_bf16_f32 v133, v86, v87
	v_cvt_pk_bf16_f32 v135, v138, v139
	global_store_dwordx4 v[66:67], v[132:135], off offset:16
	ds_read_u16 v158, v99 offset:9504
	ds_read_u16 v159, v99 offset:10032
	ds_read_u16 v160, v99 offset:43296
	ds_read_u16 v161, v99 offset:43824
	v_add_f32_e32 v69, v131, v68
	v_mul_f32_e32 v69, 0x3fb8aa3b, v69
	v_exp_f32_e32 v69, v69
	s_waitcnt lgkmcnt(11)
	v_lshlrev_b32_e32 v70, 16, v154
	v_mul_f32_e32 v71, 0x3d800000, v70
	v_rcp_f32_e32 v70, v69
	v_mul_f32_e32 v69, v69, v71
	v_cvt_pk_bf16_f32 v69, v69, s0
	ds_write_b16 v99, v69 offset:8448
	v_add_f32_e32 v69, v130, v68
	v_mul_f32_e32 v69, 0x3fb8aa3b, v69
	v_exp_f32_e32 v69, v69
	s_waitcnt lgkmcnt(11)
	v_lshlrev_b32_e32 v71, 16, v155
	v_mul_f32_e32 v86, 0x3d800000, v71
	v_rcp_f32_e32 v71, v69
	v_mul_f32_e32 v69, v69, v86
	v_cvt_pk_bf16_f32 v69, v69, s0
	ds_write_b16 v99, v69 offset:8976
	s_waitcnt lgkmcnt(11)
	v_lshlrev_b32_e32 v86, 16, v156
	s_waitcnt lgkmcnt(10)
	v_lshlrev_b32_e32 v87, 16, v157
	v_pk_mul_f32 v[86:87], v[70:71], v[86:87]
	s_nop 0
	v_pk_mul_f32 v[70:71], v[64:65], v[86:87] op_sel_hi:[0,1]
	v_cvt_pk_bf16_f32 v86, v86, s0
	v_cvt_pk_bf16_f32 v69, v87, s0
	ds_write_b16 v99, v86 offset:42240
	ds_write_b16 v99, v69 offset:42768
	ds_read_u16 v154, v99 offset:10560
	ds_read_u16 v155, v99 offset:11088
	ds_read_u16 v156, v99 offset:44352
	ds_read_u16 v157, v99 offset:44880
	v_add_f32_e32 v69, v129, v68
	v_mul_f32_e32 v69, 0x3fb8aa3b, v69
	v_exp_f32_e32 v69, v69
	s_waitcnt lgkmcnt(11)
	v_lshlrev_b32_e32 v86, 16, v158
	v_mul_f32_e32 v87, 0x3d800000, v86
	v_rcp_f32_e32 v86, v69
	v_mul_f32_e32 v69, v69, v87
	v_cvt_pk_bf16_f32 v69, v69, s0
	ds_write_b16 v99, v69 offset:9504
	v_add_f32_e32 v69, v128, v68
	v_mul_f32_e32 v69, 0x3fb8aa3b, v69
	v_exp_f32_e32 v69, v69
	s_waitcnt lgkmcnt(11)
	v_lshlrev_b32_e32 v87, 16, v159
	v_mul_f32_e32 v128, 0x3d800000, v87
	v_rcp_f32_e32 v87, v69
	v_mul_f32_e32 v69, v69, v128
	v_cvt_pk_bf16_f32 v69, v69, s0
	ds_write_b16 v99, v69 offset:10032
	s_waitcnt lgkmcnt(11)
	v_lshlrev_b32_e32 v128, 16, v160
	s_waitcnt lgkmcnt(10)
	v_lshlrev_b32_e32 v129, 16, v161
	v_pk_mul_f32 v[128:129], v[86:87], v[128:129]
	s_nop 0
	v_pk_mul_f32 v[86:87], v[64:65], v[128:129] op_sel_hi:[0,1]
	v_cvt_pk_bf16_f32 v128, v128, s0
	v_cvt_pk_bf16_f32 v69, v129, s0
	ds_write_b16 v99, v128 offset:43296
	ds_write_b16 v99, v69 offset:43824
	v_add_f32_e32 v69, v127, v68
	ds_read_u16 v158, v99 offset:11616
	ds_read_u16 v159, v99 offset:12144
	ds_read_u16 v160, v99 offset:45408
	ds_read_u16 v161, v99 offset:45936
	v_mul_f32_e32 v69, 0x3fb8aa3b, v69
	v_exp_f32_e32 v69, v69
	s_waitcnt lgkmcnt(11)
	v_lshlrev_b32_e32 v127, 16, v154
	v_mul_f32_e32 v127, 0x3d800000, v127
	v_rcp_f32_e32 v128, v69
	v_mul_f32_e32 v69, v69, v127
	v_cvt_pk_bf16_f32 v69, v69, s0
	ds_write_b16 v99, v69 offset:10560
	v_add_f32_e32 v69, v126, v68
	v_mul_f32_e32 v69, 0x3fb8aa3b, v69
	v_exp_f32_e32 v69, v69
	s_waitcnt lgkmcnt(11)
	v_lshlrev_b32_e32 v126, 16, v155
	v_mul_f32_e32 v126, 0x3d800000, v126
	v_rcp_f32_e32 v129, v69
	v_mul_f32_e32 v69, v69, v126
	v_cvt_pk_bf16_f32 v69, v69, s0
	ds_write_b16 v99, v69 offset:11088
	s_waitcnt lgkmcnt(11)
	v_lshlrev_b32_e32 v126, 16, v156
	s_waitcnt lgkmcnt(10)
	v_lshlrev_b32_e32 v127, 16, v157
	v_pk_mul_f32 v[126:127], v[128:129], v[126:127]
	s_nop 0
	v_pk_mul_f32 v[128:129], v[64:65], v[126:127] op_sel_hi:[0,1]
	v_cvt_pk_bf16_f32 v126, v126, s0
	v_cvt_pk_bf16_f32 v69, v127, s0
	ds_write_b16 v99, v126 offset:44352
	ds_write_b16 v99, v69 offset:44880
	v_add_f32_e32 v69, v125, v68
	ds_read_u16 v154, v99 offset:12672
	ds_read_u16 v155, v99 offset:13200
	ds_read_u16 v156, v99 offset:46464
	ds_read_u16 v157, v99 offset:46992
	v_mul_f32_e32 v69, 0x3fb8aa3b, v69
	v_exp_f32_e32 v69, v69
	v_cvt_pk_bf16_f32 v128, v128, v129
	s_waitcnt lgkmcnt(11)
	v_lshlrev_b32_e32 v125, 16, v158
	v_mul_f32_e32 v125, 0x3d800000, v125
	v_rcp_f32_e32 v126, v69
	v_mul_f32_e32 v69, v69, v125
	v_cvt_pk_bf16_f32 v69, v69, s0
	ds_write_b16 v99, v69 offset:11616
	v_add_f32_e32 v69, v91, v68
	v_mul_f32_e32 v69, 0x3fb8aa3b, v69
	v_exp_f32_e32 v69, v69
	s_waitcnt lgkmcnt(11)
	v_lshlrev_b32_e32 v91, 16, v159
	v_mul_f32_e32 v91, 0x3d800000, v91
	v_rcp_f32_e32 v127, v69
	v_mul_f32_e32 v69, v69, v91
	v_cvt_pk_bf16_f32 v69, v69, s0
	ds_write_b16 v99, v69 offset:12144
	s_waitcnt lgkmcnt(11)
	v_lshlrev_b32_e32 v130, 16, v160
	s_waitcnt lgkmcnt(10)
	v_lshlrev_b32_e32 v131, 16, v161
	v_pk_mul_f32 v[126:127], v[126:127], v[130:131]
	s_nop 0
	v_pk_mul_f32 v[130:131], v[64:65], v[126:127] op_sel_hi:[0,1]
	v_cvt_pk_bf16_f32 v91, v126, s0
	v_cvt_pk_bf16_f32 v69, v127, s0
	ds_write_b16 v99, v91 offset:45408
	ds_write_b16 v99, v69 offset:45936
	v_cvt_pk_bf16_f32 v126, v70, v71
	v_cvt_pk_bf16_f32 v127, v86, v87
	v_cvt_pk_bf16_f32 v129, v130, v131
	global_store_dwordx4 v[66:67], v[126:129], off offset:32
	ds_read_u16 v158, v99 offset:13728
	ds_read_u16 v159, v99 offset:14256
	ds_read_u16 v160, v99 offset:47520
	ds_read_u16 v161, v99 offset:48048
	v_add_f32_e32 v69, v90, v68
	v_mul_f32_e32 v69, 0x3fb8aa3b, v69
	v_exp_f32_e32 v69, v69
	v_add_f32_e32 v65, v65, v68
	s_waitcnt lgkmcnt(11)
	v_lshlrev_b32_e32 v70, 16, v154
	v_mul_f32_e32 v70, 0x3d800000, v70
	v_rcp_f32_e32 v90, v69
	v_mul_f32_e32 v69, v69, v70
	v_cvt_pk_bf16_f32 v69, v69, s0
	ds_write_b16 v99, v69 offset:12672
	v_add_f32_e32 v69, v89, v68
	v_mul_f32_e32 v69, 0x3fb8aa3b, v69
	v_exp_f32_e32 v69, v69
	v_mul_f32_e32 v65, 0x3fb8aa3b, v65
	s_waitcnt lgkmcnt(11)
	v_lshlrev_b32_e32 v70, 16, v155
	v_exp_f32_e32 v126, v65
	v_add_f32_e32 v65, v122, v68
	v_mul_f32_e32 v70, 0x3d800000, v70
	v_mul_f32_e32 v65, 0x3fb8aa3b, v65
	v_rcp_f32_e32 v91, v69
	v_mul_f32_e32 v69, v69, v70
	v_exp_f32_e32 v122, v65
	v_add_f32_e32 v65, v121, v68
	v_cvt_pk_bf16_f32 v69, v69, s0
	v_mul_f32_e32 v65, 0x3fb8aa3b, v65
	ds_write_b16 v99, v69 offset:13200
	v_add_f32_e32 v69, v88, v68
	v_exp_f32_e32 v121, v65
	v_add_f32_e32 v65, v123, v68
	v_mul_f32_e32 v69, 0x3fb8aa3b, v69
	v_mul_f32_e32 v65, 0x3fb8aa3b, v65
	v_exp_f32_e32 v125, v69
	v_exp_f32_e32 v123, v65
	v_add_f32_e32 v65, v124, v68
	v_rcp_f32_e32 v88, v125
	v_rcp_f32_e32 v89, v126
	v_rcp_f32_e32 v86, v122
	s_waitcnt lgkmcnt(11)
	v_lshlrev_b32_e32 v68, 16, v156
	s_waitcnt lgkmcnt(10)
	v_lshlrev_b32_e32 v69, 16, v157
	v_pk_mul_f32 v[68:69], v[90:91], v[68:69]
	v_rcp_f32_e32 v87, v121
	v_cvt_pk_bf16_f32 v90, v68, s0
	ds_write_b16 v99, v90 offset:46464
	v_cvt_pk_bf16_f32 v90, v69, s0
	ds_write_b16 v99, v90 offset:46992
	ds_read_u16 v154, v99 offset:14784
	ds_read_u16 v155, v99 offset:15312
	ds_read_u16 v156, v99 offset:48576
	ds_read_u16 v157, v99 offset:49104
	v_mul_f32_e32 v65, 0x3fb8aa3b, v65
	v_exp_f32_e32 v65, v65
	v_rcp_f32_e32 v70, v123
	s_waitcnt lgkmcnt(11)
	v_lshlrev_b32_e32 v90, 16, v158
	v_mul_f32_e32 v90, 0x3d800000, v90
	v_mul_f32_e32 v90, v125, v90
	v_cvt_pk_bf16_f32 v90, v90, s0
	ds_write_b16 v99, v90 offset:13728
	v_rcp_f32_e32 v71, v65
	v_pk_mul_f32 v[68:69], v[64:65], v[68:69] op_sel_hi:[0,1]
	v_cvt_pk_bf16_f32 v68, v68, v69
	s_waitcnt lgkmcnt(11)
	v_lshlrev_b32_e32 v90, 16, v159
	v_mul_f32_e32 v90, 0x3d800000, v90
	v_mul_f32_e32 v90, v126, v90
	v_cvt_pk_bf16_f32 v90, v90, s0
	ds_write_b16 v99, v90 offset:14256
	s_waitcnt lgkmcnt(11)
	v_lshlrev_b32_e32 v90, 16, v160
	s_waitcnt lgkmcnt(10)
	v_lshlrev_b32_e32 v91, 16, v161
	v_pk_mul_f32 v[88:89], v[88:89], v[90:91]
	s_nop 0
	v_cvt_pk_bf16_f32 v90, v88, s0
	ds_write_b16 v99, v90 offset:47520
	v_cvt_pk_bf16_f32 v90, v89, s0
	ds_write_b16 v99, v90 offset:48048
	ds_read_u16 v158, v99 offset:15840
	ds_read_u16 v159, v99 offset:16368
	ds_read_u16 v160, v99 offset:49632
	ds_read_u16 v161, v99 offset:50160
	v_pk_mul_f32 v[88:89], v[64:65], v[88:89] op_sel_hi:[0,1]
	v_cvt_pk_bf16_f32 v69, v88, v89
	v_lshl_add_u32 v88, v80, 1, 0
	s_waitcnt lgkmcnt(11)
	v_lshlrev_b32_e32 v90, 16, v154
	v_mul_f32_e32 v90, 0x3d800000, v90
	v_mul_f32_e32 v90, v122, v90
	v_cvt_pk_bf16_f32 v90, v90, s0
	ds_write_b16 v99, v90 offset:14784
	s_waitcnt lgkmcnt(11)
	v_lshlrev_b32_e32 v90, 16, v155
	v_mul_f32_e32 v90, 0x3d800000, v90
	v_mul_f32_e32 v90, v121, v90
	v_cvt_pk_bf16_f32 v90, v90, s0
	ds_write_b16 v99, v90 offset:15312
	s_waitcnt lgkmcnt(11)
	v_lshlrev_b32_e32 v90, 16, v156
	s_waitcnt lgkmcnt(10)
	v_lshlrev_b32_e32 v91, 16, v157
	v_pk_mul_f32 v[86:87], v[86:87], v[90:91]
	s_nop 0
	v_cvt_pk_bf16_f32 v90, v86, s0
	ds_write_b16 v99, v90 offset:48576
	v_cvt_pk_bf16_f32 v90, v87, s0
	ds_write_b16 v99, v90 offset:49104
	s_waitcnt lgkmcnt(7)
	v_lshlrev_b32_e32 v90, 16, v158
	v_mul_f32_e32 v90, 0x3d800000, v90
	v_mul_f32_e32 v90, v123, v90
	v_cvt_pk_bf16_f32 v90, v90, s0
	ds_write_b16 v99, v90 offset:15840
	s_waitcnt lgkmcnt(7)
	v_lshlrev_b32_e32 v90, 16, v159
	v_mul_f32_e32 v90, 0x3d800000, v90
	v_mul_f32_e32 v65, v65, v90
	v_cvt_pk_bf16_f32 v65, v65, s0
	ds_write_b16 v99, v65 offset:16368
	v_pk_mul_f32 v[86:87], v[64:65], v[86:87] op_sel_hi:[0,1]
	s_waitcnt lgkmcnt(6)
	v_lshlrev_b32_e32 v91, 16, v161
	v_lshlrev_b32_e32 v90, 16, v160
	v_pk_mul_f32 v[70:71], v[70:71], v[90:91]
	s_nop 0
	v_cvt_pk_bf16_f32 v65, v70, s0
	ds_write_b16 v99, v65 offset:49632
	v_cvt_pk_bf16_f32 v65, v71, s0
	ds_write_b16 v99, v65 offset:50160
	v_pk_mul_f32 v[64:65], v[64:65], v[70:71] op_sel_hi:[0,1]
	v_cvt_pk_bf16_f32 v70, v86, v87
	v_cvt_pk_bf16_f32 v71, v64, v65
	global_store_dwordx4 v[66:67], v[68:71], off offset:48
	s_waitcnt lgkmcnt(0)
	s_barrier
	s_lshl_b32 s0, s0, 1
	ds_read_b128 v[64:67], v94
	s_add_u32 s4, s1, s0
	s_addc_u32 s5, s5, 0
	v_lshl_add_u64 v[68:69], s[4:5], 0, v[78:79]
	v_lshl_add_u64 v[68:69], v[68:69], 0, v[96:97]
	s_waitcnt lgkmcnt(0)
	global_store_dwordx4 v[68:69], v[64:67], off
	ds_read_b128 v[64:67], v95
	v_lshl_add_u64 v[68:69], s[4:5], 0, v[76:77]
	v_lshl_add_u64 v[68:69], v[68:69], 0, v[96:97]
	v_readlane_b32 s1, v253, 18
	s_add_i32 s14, s10, 1
	s_waitcnt lgkmcnt(0)
	global_store_dwordx4 v[68:69], v[64:67], off
	ds_read_b128 v[64:67], v93
	v_lshl_add_u64 v[68:69], s[4:5], 0, v[74:75]
	v_lshl_add_u64 v[68:69], v[68:69], 0, v[96:97]
	s_ashr_i32 s15, s14, 31
	s_waitcnt lgkmcnt(0)
	global_store_dwordx4 v[68:69], v[64:67], off
	ds_read_b128 v[64:67], v92
	v_lshl_add_u64 v[68:69], s[4:5], 0, v[72:73]
	v_lshl_add_u64 v[68:69], v[68:69], 0, v[96:97]
	s_waitcnt lgkmcnt(0)
	global_store_dwordx4 v[68:69], v[64:67], off
	s_nop 1
	v_or_b32_e32 v64, s27, v81
	v_mad_u64_u32 v[86:87], s[4:5], v64, s2, v[88:89]
	v_or_b32_e32 v87, s1, v81
	v_mad_u32_u24 v89, v87, s2, v88
	ds_read_b128 v[68:71], v86
	ds_read_b128 v[64:67], v89 offset:33792
	ds_read_b128 v[122:125], v86 offset:64
	ds_read_b128 v[126:129], v89 offset:33856
	s_waitcnt lgkmcnt(2)
	v_mfma_f32_16x16x32_bf16 v[64:67], v[68:71], v[64:67], 0
	v_readlane_b32 s1, v254, 35
	s_waitcnt lgkmcnt(0)
	v_mfma_f32_16x16x32_bf16 v[64:67], v[122:125], v[126:129], v[64:67]
	ds_read_b128 v[126:129], v86 offset:128
	ds_read_b128 v[130:133], v89 offset:33920
	s_waitcnt lgkmcnt(0)
	v_mfma_f32_16x16x32_bf16 v[64:67], v[126:129], v[130:133], v[64:67]
	ds_read_b128 v[130:133], v86 offset:192
	ds_read_b128 v[134:137], v89 offset:33984
	s_waitcnt lgkmcnt(0)
	v_mfma_f32_16x16x32_bf16 v[64:67], v[130:133], v[134:137], v[64:67]
	ds_read_b128 v[134:137], v86 offset:256
	ds_read_b128 v[138:141], v89 offset:34048
	s_waitcnt lgkmcnt(0)
	v_mfma_f32_16x16x32_bf16 v[64:67], v[134:137], v[138:141], v[64:67]
	ds_read_b128 v[138:141], v86 offset:320
	ds_read_b128 v[142:145], v89 offset:34112
	s_waitcnt lgkmcnt(0)
	v_mfma_f32_16x16x32_bf16 v[64:67], v[138:141], v[142:145], v[64:67]
	ds_read_b128 v[142:145], v86 offset:384
	ds_read_b128 v[146:149], v89 offset:34176
	s_waitcnt lgkmcnt(0)
	v_mfma_f32_16x16x32_bf16 v[64:67], v[142:145], v[146:149], v[64:67]
	ds_read_b128 v[146:149], v86 offset:448
	ds_read_b128 v[150:153], v89 offset:34240
	s_waitcnt lgkmcnt(0)
	v_mfma_f32_16x16x32_bf16 v[64:67], v[146:149], v[150:153], v[64:67]
	ds_read_b128 v[150:153], v89 offset:42240
	s_waitcnt lgkmcnt(0)
	v_mfma_f32_16x16x32_bf16 v[68:71], v[68:71], v[150:153], 0
	ds_read_b128 v[150:153], v89 offset:42304
	s_waitcnt lgkmcnt(0)
	v_mfma_f32_16x16x32_bf16 v[68:71], v[122:125], v[150:153], v[68:71]
	ds_read_b128 v[122:125], v89 offset:42368
	s_waitcnt lgkmcnt(0)
	v_mfma_f32_16x16x32_bf16 v[68:71], v[126:129], v[122:125], v[68:71]
	ds_read_b128 v[122:125], v89 offset:42432
	s_waitcnt lgkmcnt(0)
	v_mfma_f32_16x16x32_bf16 v[68:71], v[130:133], v[122:125], v[68:71]
	ds_read_b128 v[122:125], v89 offset:42496
	s_waitcnt lgkmcnt(0)
	v_mfma_f32_16x16x32_bf16 v[68:71], v[134:137], v[122:125], v[68:71]
	ds_read_b128 v[122:125], v89 offset:42560
	s_waitcnt lgkmcnt(0)
	v_mfma_f32_16x16x32_bf16 v[68:71], v[138:141], v[122:125], v[68:71]
	ds_read_b128 v[122:125], v89 offset:42624
	s_waitcnt lgkmcnt(0)
	v_mfma_f32_16x16x32_bf16 v[68:71], v[142:145], v[122:125], v[68:71]
	ds_read_b128 v[122:125], v89 offset:42688
	s_waitcnt lgkmcnt(0)
	s_barrier
	ds_write_b128 v94, v[48:51]
	ds_write_b128 v95, v[52:55]
	ds_write_b128 v93, v[56:59]
	ds_write_b128 v92, v[60:63]
	v_add3_u32 v56, s1, v119, v120
	ds_read2_b32 v[52:53], v56 offset1:4
	ds_read2_b32 v[54:55], v56 offset0:8 offset1:12
	s_waitcnt lgkmcnt(1)
	v_mfma_f32_16x16x4_f32 v[48:51], v112, v52, 0
	s_mov_b32 s1, 0x3d800000
	v_mfma_f32_16x16x4_f32 v[48:51], v107, v53, v[48:51]
	s_waitcnt lgkmcnt(0)
	v_mfma_f32_16x16x4_f32 v[48:51], v108, v54, v[48:51]
	v_mfma_f32_16x16x4_f32 v[48:51], v110, v55, v[48:51]
	v_mfma_f32_16x16x32_bf16 v[68:71], v[146:149], v[122:125], v[68:71]
	s_nop 8
	ds_write_b128 v118, v[48:51] offset:33792
	v_mfma_f32_16x16x4_f32 v[48:51], v109, v52, 0
	v_mfma_f32_16x16x4_f32 v[48:51], v111, v53, v[48:51]
	v_mfma_f32_16x16x4_f32 v[48:51], v113, v54, v[48:51]
	s_waitcnt vmcnt(9)
	v_mfma_f32_16x16x4_f32 v[48:51], v106, v55, v[48:51]
	s_nop 9
	ds_write_b128 v118, v[48:51] offset:33856
	v_add_u32_e32 v48, 0x800, v56
	ds_read2_b32 v[52:53], v48 offset0:16 offset1:20
	ds_read2_b32 v[54:55], v48 offset0:24 offset1:28
	s_waitcnt lgkmcnt(1)
	v_mfma_f32_16x16x4_f32 v[48:51], v112, v52, 0
	v_mfma_f32_16x16x4_f32 v[48:51], v107, v53, v[48:51]
	s_waitcnt lgkmcnt(0)
	v_mfma_f32_16x16x4_f32 v[48:51], v108, v54, v[48:51]
	v_mfma_f32_16x16x4_f32 v[48:51], v110, v55, v[48:51]
	s_nop 9
	ds_write_b128 v117, v[48:51] offset:33792
	v_mfma_f32_16x16x4_f32 v[48:51], v109, v52, 0
	v_mfma_f32_16x16x4_f32 v[48:51], v111, v53, v[48:51]
	v_mfma_f32_16x16x4_f32 v[48:51], v113, v54, v[48:51]
	v_mfma_f32_16x16x4_f32 v[48:51], v106, v55, v[48:51]
	s_nop 9
	ds_write_b128 v117, v[48:51] offset:33856
	v_add_u32_e32 v48, 0x1000, v56
	ds_read2_b32 v[52:53], v48 offset0:32 offset1:36
	ds_read2_b32 v[54:55], v48 offset0:40 offset1:44
	s_waitcnt lgkmcnt(1)
	v_mfma_f32_16x16x4_f32 v[48:51], v112, v52, 0
	v_mfma_f32_16x16x4_f32 v[48:51], v107, v53, v[48:51]
	s_waitcnt lgkmcnt(0)
	v_mfma_f32_16x16x4_f32 v[48:51], v108, v54, v[48:51]
	v_mfma_f32_16x16x4_f32 v[48:51], v110, v55, v[48:51]
	s_nop 9
	ds_write_b128 v116, v[48:51] offset:33792
	v_mfma_f32_16x16x4_f32 v[48:51], v109, v52, 0
	v_mfma_f32_16x16x4_f32 v[48:51], v111, v53, v[48:51]
	v_mfma_f32_16x16x4_f32 v[48:51], v113, v54, v[48:51]
	v_mfma_f32_16x16x4_f32 v[48:51], v106, v55, v[48:51]
	s_nop 9
	ds_write_b128 v116, v[48:51] offset:33856
	v_add_u32_e32 v48, 0x1800, v56
	ds_read2_b32 v[52:53], v48 offset0:48 offset1:52
	ds_read2_b32 v[54:55], v48 offset0:56 offset1:60
	s_waitcnt lgkmcnt(1)
	v_mfma_f32_16x16x4_f32 v[48:51], v112, v52, 0
	v_mfma_f32_16x16x4_f32 v[48:51], v107, v53, v[48:51]
	s_waitcnt lgkmcnt(0)
	v_mfma_f32_16x16x4_f32 v[48:51], v108, v54, v[48:51]
	v_mfma_f32_16x16x4_f32 v[48:51], v110, v55, v[48:51]
	s_nop 9
	ds_write_b128 v114, v[48:51] offset:33792
	v_mfma_f32_16x16x4_f32 v[48:51], v109, v52, 0
	v_mfma_f32_16x16x4_f32 v[48:51], v111, v53, v[48:51]
	v_mfma_f32_16x16x4_f32 v[48:51], v113, v54, v[48:51]
	v_mfma_f32_16x16x4_f32 v[48:51], v106, v55, v[48:51]
	s_nop 9
	ds_write_b128 v114, v[48:51] offset:33856
	s_waitcnt lgkmcnt(0)
	s_barrier
	ds_read_b32 v48, v115 offset:32240
	s_waitcnt vmcnt(8) lgkmcnt(0)
	v_add_f32_e32 v48, v100, v48
	v_min_f32_e32 v49, 0, v48
	v_mul_f32_e64 v48, |v48|, s25
	v_exp_f32_e32 v48, v48
	s_nop 0
	v_add_f32_e32 v48, 1.0, v48
	v_log_f32_e32 v48, v48
	s_nop 0
	v_fmac_f32_e32 v49, 0xbf317218, v48
	v_fma_f32 v48, v49, s1, 0
	ds_read_b32 v49, v103 offset:64992
	s_waitcnt lgkmcnt(0)
	v_add_f32_e32 v49, v100, v49
	v_min_f32_e32 v50, 0, v49
	v_mul_f32_e64 v49, |v49|, s25
	v_exp_f32_e32 v49, v49
	s_nop 0
	v_add_f32_e32 v49, 1.0, v49
	v_log_f32_e32 v49, v49
	s_nop 0
	v_fmac_f32_e32 v50, 0xbf317218, v49
	v_fmamk_f32 v49, v50, 0x3d800000, v48
	ds_read_b32 v50, v103 offset:63952
	s_waitcnt lgkmcnt(0)
	v_add_f32_e32 v50, v100, v50
	v_min_f32_e32 v51, 0, v50
	v_mul_f32_e64 v50, |v50|, s25
	v_exp_f32_e32 v50, v50
	s_nop 0
	v_add_f32_e32 v50, 1.0, v50
	v_log_f32_e32 v50, v50
	s_nop 0
	v_fmac_f32_e32 v51, 0xbf317218, v50
	v_fmamk_f32 v50, v51, 0x3d800000, v49
	ds_read_b32 v51, v103 offset:62912
	s_waitcnt lgkmcnt(0)
	v_add_f32_e32 v51, v100, v51
	v_min_f32_e32 v52, 0, v51
	v_mul_f32_e64 v51, |v51|, s25
	v_exp_f32_e32 v51, v51
	s_nop 0
	v_add_f32_e32 v51, 1.0, v51
	v_log_f32_e32 v51, v51
	s_nop 0
	v_fmac_f32_e32 v52, 0xbf317218, v51
	v_fmamk_f32 v51, v52, 0x3d800000, v50
	ds_read_b32 v52, v103 offset:61872
	s_waitcnt lgkmcnt(0)
	v_add_f32_e32 v52, v100, v52
	v_min_f32_e32 v53, 0, v52
	v_mul_f32_e64 v52, |v52|, s25
	v_exp_f32_e32 v52, v52
	s_nop 0
	v_add_f32_e32 v52, 1.0, v52
	v_log_f32_e32 v52, v52
	s_nop 0
	v_fmac_f32_e32 v53, 0xbf317218, v52
	v_fmamk_f32 v52, v53, 0x3d800000, v51
	ds_read_b32 v53, v103 offset:60832
	s_waitcnt lgkmcnt(0)
	v_add_f32_e32 v53, v100, v53
	v_min_f32_e32 v54, 0, v53
	v_mul_f32_e64 v53, |v53|, s25
	v_exp_f32_e32 v53, v53
	s_nop 0
	v_add_f32_e32 v53, 1.0, v53
	v_log_f32_e32 v53, v53
	s_nop 0
	v_fmac_f32_e32 v54, 0xbf317218, v53
	v_fmamk_f32 v53, v54, 0x3d800000, v52
	ds_read_b32 v54, v103 offset:59792
	s_waitcnt lgkmcnt(0)
	v_add_f32_e32 v54, v100, v54
	v_min_f32_e32 v55, 0, v54
	v_mul_f32_e64 v54, |v54|, s25
	v_exp_f32_e32 v54, v54
	s_nop 0
	v_add_f32_e32 v54, 1.0, v54
	v_log_f32_e32 v54, v54
	s_nop 0
	v_fmac_f32_e32 v55, 0xbf317218, v54
	v_fmamk_f32 v54, v55, 0x3d800000, v53
	ds_read_b32 v55, v103 offset:58752
	s_waitcnt lgkmcnt(0)
	v_add_f32_e32 v55, v100, v55
	v_min_f32_e32 v56, 0, v55
	v_mul_f32_e64 v55, |v55|, s25
	v_exp_f32_e32 v55, v55
	s_nop 0
	v_add_f32_e32 v55, 1.0, v55
	v_log_f32_e32 v55, v55
	s_nop 0
	v_fmac_f32_e32 v56, 0xbf317218, v55
	ds_read_b32 v55, v103 offset:57712
	v_fmamk_f32 v56, v56, 0x3d800000, v54
	s_waitcnt lgkmcnt(0)
	v_add_f32_e32 v55, v100, v55
	v_min_f32_e32 v57, 0, v55
	v_mul_f32_e64 v55, |v55|, s25
	v_exp_f32_e32 v55, v55
	s_nop 0
	v_add_f32_e32 v55, 1.0, v55
	v_log_f32_e32 v55, v55
	s_nop 0
	v_fmac_f32_e32 v57, 0xbf317218, v55
	v_fmamk_f32 v55, v57, 0x3d800000, v56
	ds_read_b32 v57, v103 offset:56672
	s_waitcnt lgkmcnt(0)
	v_add_f32_e32 v57, v100, v57
	v_min_f32_e32 v58, 0, v57
	v_mul_f32_e64 v57, |v57|, s25
	v_exp_f32_e32 v57, v57
	s_nop 0
	v_add_f32_e32 v57, 1.0, v57
	v_log_f32_e32 v57, v57
	s_nop 0
	v_fmac_f32_e32 v58, 0xbf317218, v57
	v_fmamk_f32 v57, v58, 0x3d800000, v55
	ds_read_b32 v58, v103 offset:55632
	s_waitcnt lgkmcnt(0)
	v_add_f32_e32 v58, v100, v58
	v_min_f32_e32 v59, 0, v58
	v_mul_f32_e64 v58, |v58|, s25
	v_exp_f32_e32 v58, v58
	s_nop 0
	v_add_f32_e32 v58, 1.0, v58
	v_log_f32_e32 v58, v58
	s_nop 0
	v_fmac_f32_e32 v59, 0xbf317218, v58
	v_fmamk_f32 v58, v59, 0x3d800000, v57
	ds_read_b32 v59, v103 offset:54592
	s_waitcnt lgkmcnt(0)
	v_add_f32_e32 v59, v100, v59
	v_min_f32_e32 v60, 0, v59
	v_mul_f32_e64 v59, |v59|, s25
	v_exp_f32_e32 v59, v59
	s_nop 0
	v_add_f32_e32 v59, 1.0, v59
	v_log_f32_e32 v59, v59
	s_nop 0
	v_fmac_f32_e32 v60, 0xbf317218, v59
	v_fmamk_f32 v59, v60, 0x3d800000, v58
	ds_read_b32 v60, v103 offset:53552
	s_waitcnt lgkmcnt(0)
	v_add_f32_e32 v60, v100, v60
	v_min_f32_e32 v61, 0, v60
	v_mul_f32_e64 v60, |v60|, s25
	v_exp_f32_e32 v60, v60
	s_nop 0
	v_add_f32_e32 v60, 1.0, v60
	v_log_f32_e32 v60, v60
	s_nop 0
	v_fmac_f32_e32 v61, 0xbf317218, v60
	v_fmamk_f32 v60, v61, 0x3d800000, v59
	ds_read_b32 v61, v103 offset:52512
	s_waitcnt lgkmcnt(0)
	v_add_f32_e32 v61, v100, v61
	v_min_f32_e32 v62, 0, v61
	v_mul_f32_e64 v61, |v61|, s25
	v_exp_f32_e32 v61, v61
	s_nop 0
	v_add_f32_e32 v61, 1.0, v61
	v_log_f32_e32 v61, v61
	s_nop 0
	v_fmac_f32_e32 v62, 0xbf317218, v61
	v_fmamk_f32 v61, v62, 0x3d800000, v60
	ds_read_b32 v62, v103 offset:51472
	s_waitcnt lgkmcnt(0)
	v_add_f32_e32 v62, v100, v62
	v_min_f32_e32 v63, 0, v62
	v_mul_f32_e64 v62, |v62|, s25
	v_exp_f32_e32 v62, v62
	s_nop 0
	v_add_f32_e32 v62, 1.0, v62
	v_log_f32_e32 v62, v62
	s_nop 0
	v_fmac_f32_e32 v63, 0xbf317218, v62
	v_fmamk_f32 v62, v63, 0x3d800000, v61
	ds_read_b32 v63, v103 offset:50432
	s_waitcnt lgkmcnt(0)
	v_add_f32_e32 v63, v100, v63
	v_min_f32_e32 v89, 0, v63
	v_mul_f32_e64 v63, |v63|, s25
	v_exp_f32_e32 v63, v63
	s_nop 0
	v_add_f32_e32 v63, 1.0, v63
	v_log_f32_e32 v63, v63
	s_nop 0
	v_fmac_f32_e32 v89, 0xbf317218, v63
	ds_read_b32 v63, v103 offset:49392
	v_fmamk_f32 v89, v89, 0x3d800000, v62
	s_waitcnt lgkmcnt(0)
	v_add_f32_e32 v63, v100, v63
	v_min_f32_e32 v90, 0, v63
	v_mul_f32_e64 v63, |v63|, s25
	v_exp_f32_e32 v63, v63
	s_nop 0
	v_add_f32_e32 v63, 1.0, v63
	v_log_f32_e32 v63, v63
	s_nop 0
	v_fmac_f32_e32 v90, 0xbf317218, v63
	v_fmamk_f32 v63, v90, 0x3d800000, v89
	ds_read_b32 v90, v103 offset:48352
	s_waitcnt lgkmcnt(0)
	v_add_f32_e32 v90, v100, v90
	v_min_f32_e32 v91, 0, v90
	v_mul_f32_e64 v90, |v90|, s25
	v_exp_f32_e32 v90, v90
	s_nop 0
	v_add_f32_e32 v90, 1.0, v90
	v_log_f32_e32 v90, v90
	s_nop 0
	v_fmac_f32_e32 v91, 0xbf317218, v90
	v_fmamk_f32 v90, v91, 0x3d800000, v63
	ds_read_b32 v91, v103 offset:47312
	s_waitcnt lgkmcnt(0)
	v_add_f32_e32 v91, v100, v91
	v_min_f32_e32 v106, 0, v91
	v_mul_f32_e64 v91, |v91|, s25
	v_exp_f32_e32 v91, v91
	s_nop 0
	v_add_f32_e32 v91, 1.0, v91
	v_log_f32_e32 v91, v91
	s_nop 0
	v_fmac_f32_e32 v106, 0xbf317218, v91
	v_fmamk_f32 v91, v106, 0x3d800000, v90
	ds_read_b32 v106, v103 offset:46272
	s_waitcnt lgkmcnt(0)
	v_add_f32_e32 v106, v100, v106
	v_min_f32_e32 v107, 0, v106
	v_mul_f32_e64 v106, |v106|, s25
	v_exp_f32_e32 v106, v106
	s_nop 0
	v_add_f32_e32 v106, 1.0, v106
	v_log_f32_e32 v106, v106
	s_nop 0
	v_fmac_f32_e32 v107, 0xbf317218, v106
	v_fmamk_f32 v106, v107, 0x3d800000, v91
	ds_read_b32 v107, v103 offset:45232
	s_waitcnt lgkmcnt(0)
	v_add_f32_e32 v107, v100, v107
	v_min_f32_e32 v108, 0, v107
	v_mul_f32_e64 v107, |v107|, s25
	v_exp_f32_e32 v107, v107
	s_nop 0
	v_add_f32_e32 v107, 1.0, v107
	v_log_f32_e32 v107, v107
	s_nop 0
	v_fmac_f32_e32 v108, 0xbf317218, v107
	v_fmamk_f32 v107, v108, 0x3d800000, v106
	ds_read_b32 v108, v103 offset:44192
	s_waitcnt lgkmcnt(0)
	v_add_f32_e32 v108, v100, v108
	v_min_f32_e32 v109, 0, v108
	v_mul_f32_e64 v108, |v108|, s25
	v_exp_f32_e32 v108, v108
	s_nop 0
	v_add_f32_e32 v108, 1.0, v108
	v_log_f32_e32 v108, v108
	s_nop 0
	v_fmac_f32_e32 v109, 0xbf317218, v108
	v_fmamk_f32 v108, v109, 0x3d800000, v107
	ds_read_b32 v109, v103 offset:43152
	s_waitcnt lgkmcnt(0)
	v_add_f32_e32 v109, v100, v109
	v_min_f32_e32 v110, 0, v109
	v_mul_f32_e64 v109, |v109|, s25
	v_exp_f32_e32 v109, v109
	s_nop 0
	v_add_f32_e32 v109, 1.0, v109
	v_log_f32_e32 v109, v109
	s_nop 0
	v_fmac_f32_e32 v110, 0xbf317218, v109
	v_fmamk_f32 v109, v110, 0x3d800000, v108
	ds_read_b32 v110, v103 offset:42112
	s_waitcnt lgkmcnt(0)
	v_add_f32_e32 v110, v100, v110
	v_min_f32_e32 v111, 0, v110
	v_mul_f32_e64 v110, |v110|, s25
	v_exp_f32_e32 v110, v110
	s_nop 0
	v_add_f32_e32 v110, 1.0, v110
	v_log_f32_e32 v110, v110
	s_nop 0
	v_fmac_f32_e32 v111, 0xbf317218, v110
	ds_read_b32 v110, v103 offset:41072
	v_fmamk_f32 v111, v111, 0x3d800000, v109
	s_waitcnt lgkmcnt(0)
	v_add_f32_e32 v110, v100, v110
	v_min_f32_e32 v112, 0, v110
	v_mul_f32_e64 v110, |v110|, s25
	v_exp_f32_e32 v110, v110
	s_nop 0
	v_add_f32_e32 v110, 1.0, v110
	v_log_f32_e32 v110, v110
	s_nop 0
	v_fmac_f32_e32 v112, 0xbf317218, v110
	v_fmamk_f32 v110, v112, 0x3d800000, v111
	ds_read_b32 v112, v103 offset:40032
	s_waitcnt lgkmcnt(0)
	v_add_f32_e32 v112, v100, v112
	v_min_f32_e32 v113, 0, v112
	v_mul_f32_e64 v112, |v112|, s25
	v_exp_f32_e32 v112, v112
	s_nop 0
	v_add_f32_e32 v112, 1.0, v112
	v_log_f32_e32 v112, v112
	s_nop 0
	v_fmac_f32_e32 v113, 0xbf317218, v112
	v_fmamk_f32 v112, v113, 0x3d800000, v110
	ds_read_b32 v113, v103 offset:38992
	s_waitcnt lgkmcnt(0)
	v_add_f32_e32 v113, v100, v113
	v_min_f32_e32 v114, 0, v113
	v_mul_f32_e64 v113, |v113|, s25
	v_exp_f32_e32 v113, v113
	s_nop 0
	v_add_f32_e32 v113, 1.0, v113
	v_log_f32_e32 v113, v113
	s_nop 0
	v_fmac_f32_e32 v114, 0xbf317218, v113
	v_fmamk_f32 v113, v114, 0x3d800000, v112
	ds_read_b32 v114, v103 offset:37952
	s_waitcnt lgkmcnt(0)
	v_add_f32_e32 v114, v100, v114
	v_min_f32_e32 v115, 0, v114
	v_mul_f32_e64 v114, |v114|, s25
	v_exp_f32_e32 v114, v114
	s_nop 0
	v_add_f32_e32 v114, 1.0, v114
	v_log_f32_e32 v114, v114
	s_nop 0
	v_fmac_f32_e32 v115, 0xbf317218, v114
	v_fmamk_f32 v114, v115, 0x3d800000, v113
	ds_read_b32 v115, v103 offset:36912
	s_waitcnt lgkmcnt(0)
	v_add_f32_e32 v115, v100, v115
	v_min_f32_e32 v116, 0, v115
	v_mul_f32_e64 v115, |v115|, s25
	v_exp_f32_e32 v115, v115
	s_nop 0
	v_add_f32_e32 v115, 1.0, v115
	v_log_f32_e32 v115, v115
	s_nop 0
	v_fmac_f32_e32 v116, 0xbf317218, v115
	v_fmamk_f32 v115, v116, 0x3d800000, v114
	ds_read_b32 v116, v103 offset:35872
	s_waitcnt lgkmcnt(0)
	v_add_f32_e32 v116, v100, v116
	v_min_f32_e32 v117, 0, v116
	v_mul_f32_e64 v116, |v116|, s25
	v_exp_f32_e32 v116, v116
	s_nop 0
	v_add_f32_e32 v116, 1.0, v116
	v_log_f32_e32 v116, v116
	s_nop 0
	v_fmac_f32_e32 v117, 0xbf317218, v116
	v_fmamk_f32 v116, v117, 0x3d800000, v115
	ds_read_b32 v117, v103 offset:34832
	ds_read_b32 v103, v103 offset:33792
	s_waitcnt lgkmcnt(1)
	v_add_f32_e32 v117, v100, v117
	v_min_f32_e32 v118, 0, v117
	v_mul_f32_e64 v117, |v117|, s25
	s_waitcnt lgkmcnt(0)
	v_add_f32_e32 v100, v100, v103
	v_exp_f32_e32 v117, v117
	v_min_f32_e32 v103, 0, v100
	v_mul_f32_e64 v100, |v100|, s25
	v_exp_f32_e32 v100, v100
	v_add_f32_e32 v117, 1.0, v117
	v_log_f32_e32 v117, v117
	v_add_f32_e32 v100, 1.0, v100
	v_log_f32_e32 v100, v100
	v_fmac_f32_e32 v118, 0xbf317218, v117
	v_fmamk_f32 v117, v118, 0x3d800000, v116
	v_fmac_f32_e32 v103, 0xbf317218, v100
	v_fmamk_f32 v100, v103, 0x3d800000, v117
	ds_write_b32 v104, v100
	s_waitcnt lgkmcnt(0)
	s_barrier
	ds_write_b128 v94, v[32:35] offset:33792
	ds_write_b128 v95, v[36:39] offset:33792
	ds_write_b128 v93, v[40:43] offset:33792
	ds_write_b128 v92, v[44:47] offset:33792
	ds_read2st64_b32 v[32:33], v105 offset1:4
	s_waitcnt lgkmcnt(0)
	v_add_f32_e32 v32, v33, v32
	v_mul_f32_e32 v32, 0x3fb8aa3b, v32
	v_exp_f32_e32 v32, v32
	s_and_saveexec_b64 s[4:5], vcc
	s_cbranch_execz .LBB0_418
	s_lshl_b64 s[28:29], s[14:15], 10
	s_add_u32 s28, s41, s28
	s_addc_u32 s29, s42, s29
	global_store_dword v102, v32, s[28:29]
	s_branch .LBB0_418
